# stack6 + trailing half's post-epilogue realign barrier deferred past the unit header to just before the K-loop (all four GEMM variants)
# baseline (speedup 1.0000x reference)
_Z4mega6Paramsii:
	s_mov_b32 s100, 0
	s_load_dwordx4 s[56:59], s[0:1], 0xa0
	s_load_dwordx2 s[34:35], s[0:1], 0xb0
	v_writelane_b32 v251, s2, 0
	s_add_u32 s2, s0, 0xb0
	s_addc_u32 s3, s1, 0
	v_writelane_b32 v251, s2, 1
	s_waitcnt lgkmcnt(0)
	s_add_u32 s12, s56, 0x6180000
	s_addc_u32 s13, s57, 0
	v_writelane_b32 v251, s3, 2
	s_sub_i32 s2, s59, s58
	s_cmp_lt_i32 s2, 2
	s_cbranch_scc1 .LBB0_5
	v_readlane_b32 s3, v251, 0
	s_mov_b32 s2, 0
	s_cmp_lg_u32 s3, 0
	v_and_b32_e32 v2, 0x3ff, v0
	s_cbranch_scc0 .LBB0_560
	v_cmp_gt_u32_e32 vcc, 4, v2
	s_and_saveexec_b64 s[2:3], vcc

.LBB0_289:
	s_add_u32 s56, s56, 0x80
	s_addc_u32 s57, s57, 0
	s_add_u32 s18, s54, 0x100
	s_addc_u32 s19, s55, 0
	s_mov_b32 s30, 0
	s_cmp_eq_u32 s100, 1
	s_cbranch_scc0 .Ldb_290
	s_mov_b32 s100, 0
	s_barrier
.Ldb_290:
.LBB0_290:
	s_add_i32 s29, s30, 2
	s_add_u32 s31, s56, 0x80
	s_addc_u32 s35, s57, 0
	s_add_i32 s72, 0, 0x10000
	s_cmp_eq_u32 s67, s30
	s_cselect_b32 s55, s1, s35
	s_cselect_b32 s54, s0, s31
	v_add_u32_e32 v144, s72, v147
	s_cselect_b32 s31, s53, s19
	s_cselect_b32 s30, s52, s18
	s_add_i32 s35, 0, 0x14000
	ds_read_b128 v[140:143], v144
	ds_read_b128 v[176:179], v144 offset:1024
	ds_read_b128 v[180:183], v144 offset:2048
	ds_read_b128 v[184:187], v144 offset:3072
	v_add_u32_e32 v144, s35, v147
	ds_read_b128 v[188:191], v144
	ds_read_b128 v[192:195], v144 offset:1024
	ds_read_b128 v[196:199], v144 offset:2048
	ds_read_b128 v[200:203], v144 offset:3072
	v_lshl_add_u64 v[144:145], s[56:57], 0, v[136:137]
	s_add_i32 m0, s58, 0xc000
	ds_read_b128 v[204:207], v169
	ds_read_b128 v[208:211], v169 offset:1024
	ds_read_b128 v[212:215], v169 offset:2048
	ds_read_b128 v[216:219], v169 offset:3072
	ds_read_b128 v[220:223], v169 offset:4096
	ds_read_b128 v[224:227], v169 offset:5120
	ds_read_b128 v[228:231], v169 offset:6144
	ds_read_b128 v[232:235], v169 offset:7168
	global_load_lds_dwordx4 v[144:145], off
	v_lshl_add_u64 v[144:145], s[56:57], 0, v[138:139]
	s_add_i32 m0, s58, 0xe000
	s_nop 0
	global_load_lds_dwordx4 v[144:145], off
	s_waitcnt vmcnt(8)
	s_waitcnt lgkmcnt(0)
	s_barrier
	s_waitcnt lgkmcnt(0)
	v_mfma_f32_16x16x32_bf16 v[126:129], v[140:143], v[204:207], v[126:129]
	v_mfma_f32_16x16x32_bf16 v[114:117], v[180:183], v[204:207], v[114:117]
	v_mfma_f32_16x16x32_bf16 v[106:109], v[140:143], v[212:215], v[106:109]
	v_mfma_f32_16x16x32_bf16 v[98:101], v[180:183], v[212:215], v[98:101]
	v_mfma_f32_16x16x32_bf16 v[90:93], v[140:143], v[220:223], v[90:93]
	v_mfma_f32_16x16x32_bf16 v[82:85], v[180:183], v[220:223], v[82:85]
	v_mfma_f32_16x16x32_bf16 v[74:77], v[140:143], v[228:231], v[74:77]
	v_mfma_f32_16x16x32_bf16 v[54:57], v[180:183], v[228:231], v[54:57]
	v_mfma_f32_16x16x32_bf16 v[126:129], v[176:179], v[208:211], v[126:129]
	v_mfma_f32_16x16x32_bf16 v[114:117], v[184:187], v[208:211], v[114:117]
	v_mfma_f32_16x16x32_bf16 v[106:109], v[176:179], v[216:219], v[106:109]
	v_mfma_f32_16x16x32_bf16 v[98:101], v[184:187], v[216:219], v[98:101]
	v_mfma_f32_16x16x32_bf16 v[90:93], v[176:179], v[224:227], v[90:93]
	v_mfma_f32_16x16x32_bf16 v[82:85], v[184:187], v[224:227], v[82:85]
	v_mfma_f32_16x16x32_bf16 v[74:77], v[176:179], v[232:235], v[74:77]
	v_mfma_f32_16x16x32_bf16 v[54:57], v[184:187], v[232:235], v[54:57]
	v_mfma_f32_16x16x32_bf16 v[118:121], v[188:191], v[204:207], v[118:121]
	v_mfma_f32_16x16x32_bf16 v[122:125], v[196:199], v[204:207], v[122:125]
	v_mfma_f32_16x16x32_bf16 v[102:105], v[188:191], v[212:215], v[102:105]
	v_mfma_f32_16x16x32_bf16 v[110:113], v[196:199], v[212:215], v[110:113]
	v_mfma_f32_16x16x32_bf16 v[86:89], v[188:191], v[220:223], v[86:89]
	v_mfma_f32_16x16x32_bf16 v[94:97], v[196:199], v[220:223], v[94:97]
	v_mfma_f32_16x16x32_bf16 v[70:73], v[188:191], v[228:231], v[70:73]
	v_mfma_f32_16x16x32_bf16 v[78:81], v[196:199], v[228:231], v[78:81]
	v_mfma_f32_16x16x32_bf16 v[118:121], v[192:195], v[208:211], v[118:121]
	v_mfma_f32_16x16x32_bf16 v[122:125], v[200:203], v[208:211], v[122:125]
	v_mfma_f32_16x16x32_bf16 v[102:105], v[192:195], v[216:219], v[102:105]
	v_mfma_f32_16x16x32_bf16 v[110:113], v[200:203], v[216:219], v[110:113]
	v_mfma_f32_16x16x32_bf16 v[86:89], v[192:195], v[224:227], v[86:89]
	v_mfma_f32_16x16x32_bf16 v[94:97], v[200:203], v[224:227], v[94:97]
	v_mfma_f32_16x16x32_bf16 v[70:73], v[192:195], v[232:235], v[70:73]
	v_mfma_f32_16x16x32_bf16 v[78:81], v[200:203], v[232:235], v[78:81]
	s_barrier
	s_add_i32 s72, s72, s23
	v_lshl_add_u64 v[144:145], s[30:31], 0, v[0:1]
	s_mov_b32 m0, s72
	ds_read_b128 v[204:207], v169 offset:16384
	ds_read_b128 v[208:211], v169 offset:17408
	ds_read_b128 v[212:215], v169 offset:18432
	ds_read_b128 v[216:219], v169 offset:19456
	ds_read_b128 v[220:223], v169 offset:20480
	ds_read_b128 v[224:227], v169 offset:21504
	ds_read_b128 v[228:231], v169 offset:22528
	ds_read_b128 v[232:235], v169 offset:23552
	global_load_lds_dwordx4 v[144:145], off
	s_add_i32 m0, s72, 0x2000
	v_lshl_add_u64 v[236:237], s[30:31], 0, v[134:135]
	s_add_u32 s30, s30, s80
	s_addc_u32 s31, s31, 0
	s_add_i32 s35, s35, s23
	global_load_lds_dwordx4 v[236:237], off
	v_lshl_add_u64 v[238:239], s[30:31], 0, v[0:1]
	s_mov_b32 m0, s35
	v_lshl_add_u64 v[240:241], s[30:31], 0, v[134:135]
	global_load_lds_dwordx4 v[238:239], off
	s_add_i32 m0, s35, 0x2000
	v_lshl_add_u64 v[242:243], s[54:55], 0, v[130:131]
	global_load_lds_dwordx4 v[240:241], off
	s_mov_b32 m0, s58
	v_lshl_add_u64 v[244:245], s[54:55], 0, v[132:133]
	global_load_lds_dwordx4 v[242:243], off
	s_mov_b32 m0, s59
	s_nop 0
	global_load_lds_dwordx4 v[244:245], off
	s_waitcnt vmcnt(8)
	s_waitcnt lgkmcnt(0)
	s_barrier
	s_waitcnt lgkmcnt(0)
	v_mfma_f32_16x16x32_bf16 v[58:61], v[140:143], v[204:207], v[58:61]
	v_mfma_f32_16x16x32_bf16 v[62:65], v[180:183], v[204:207], v[62:65]
	v_mfma_f32_16x16x32_bf16 v[38:41], v[140:143], v[212:215], v[38:41]
	v_mfma_f32_16x16x32_bf16 v[42:45], v[180:183], v[212:215], v[42:45]
	v_mfma_f32_16x16x32_bf16 v[18:21], v[140:143], v[220:223], v[18:21]
	v_mfma_f32_16x16x32_bf16 v[26:29], v[180:183], v[220:223], v[26:29]
	v_mfma_f32_16x16x32_bf16 v[2:5], v[140:143], v[228:231], v[2:5]
	v_mfma_f32_16x16x32_bf16 v[6:9], v[180:183], v[228:231], v[6:9]
	v_mfma_f32_16x16x32_bf16 v[58:61], v[176:179], v[208:211], v[58:61]
	v_mfma_f32_16x16x32_bf16 v[62:65], v[184:187], v[208:211], v[62:65]
	v_mfma_f32_16x16x32_bf16 v[38:41], v[176:179], v[216:219], v[38:41]
	v_mfma_f32_16x16x32_bf16 v[42:45], v[184:187], v[216:219], v[42:45]
	v_mfma_f32_16x16x32_bf16 v[18:21], v[176:179], v[224:227], v[18:21]
	v_mfma_f32_16x16x32_bf16 v[26:29], v[184:187], v[224:227], v[26:29]
	v_mfma_f32_16x16x32_bf16 v[2:5], v[176:179], v[232:235], v[2:5]
	v_mfma_f32_16x16x32_bf16 v[6:9], v[184:187], v[232:235], v[6:9]
	v_mfma_f32_16x16x32_bf16 v[50:53], v[188:191], v[204:207], v[50:53]
	v_mfma_f32_16x16x32_bf16 v[66:69], v[196:199], v[204:207], v[66:69]
	v_mfma_f32_16x16x32_bf16 v[34:37], v[188:191], v[212:215], v[34:37]
	v_mfma_f32_16x16x32_bf16 v[46:49], v[196:199], v[212:215], v[46:49]
	v_mfma_f32_16x16x32_bf16 v[14:17], v[188:191], v[220:223], v[14:17]
	v_mfma_f32_16x16x32_bf16 v[30:33], v[196:199], v[220:223], v[30:33]
	v_mfma_f32_16x16x32_bf16 v[10:13], v[188:191], v[228:231], v[10:13]
	v_mfma_f32_16x16x32_bf16 v[22:25], v[196:199], v[228:231], v[22:25]
	v_mfma_f32_16x16x32_bf16 v[50:53], v[192:195], v[208:211], v[50:53]
	v_mfma_f32_16x16x32_bf16 v[66:69], v[200:203], v[208:211], v[66:69]
	v_mfma_f32_16x16x32_bf16 v[34:37], v[192:195], v[216:219], v[34:37]
	v_mfma_f32_16x16x32_bf16 v[46:49], v[200:203], v[216:219], v[46:49]
	v_mfma_f32_16x16x32_bf16 v[14:17], v[192:195], v[224:227], v[14:17]
	v_mfma_f32_16x16x32_bf16 v[30:33], v[200:203], v[224:227], v[30:33]
	v_mfma_f32_16x16x32_bf16 v[10:13], v[192:195], v[232:235], v[10:13]
	v_mfma_f32_16x16x32_bf16 v[22:25], v[200:203], v[232:235], v[22:25]
	s_barrier
	s_add_i32 s35, 0, 0x18000
	s_add_i32 s72, 0, 0x1c000
	v_add_u32_e32 v184, s35, v147
	v_add_u32_e32 v200, s72, v147
	ds_read_b128 v[140:143], v184
	ds_read_b128 v[176:179], v184 offset:1024
	ds_read_b128 v[180:183], v184 offset:2048
	ds_read_b128 v[184:187], v184 offset:3072
	ds_read_b128 v[188:191], v200
	ds_read_b128 v[192:195], v200 offset:1024
	ds_read_b128 v[196:199], v200 offset:2048
	ds_read_b128 v[200:203], v200 offset:3072
	s_add_u32 s30, s54, s80
	s_addc_u32 s31, s55, 0
	s_mov_b32 m0, s60
	v_lshl_add_u64 v[246:247], s[30:31], 0, v[130:131]
	ds_read_b128 v[204:207], v169 offset:32768
	ds_read_b128 v[208:211], v169 offset:33792
	ds_read_b128 v[212:215], v169 offset:34816
	ds_read_b128 v[216:219], v169 offset:35840
	ds_read_b128 v[220:223], v169 offset:36864
	ds_read_b128 v[224:227], v169 offset:37888
	ds_read_b128 v[228:231], v169 offset:38912
	ds_read_b128 v[232:235], v169 offset:39936
	global_load_lds_dwordx4 v[246:247], off
	v_lshl_add_u64 v[246:247], s[30:31], 0, v[132:133]
	s_mov_b32 m0, s61
	s_nop 0
	global_load_lds_dwordx4 v[246:247], off
	s_waitcnt vmcnt(8)
	s_waitcnt lgkmcnt(0)
	s_barrier
	s_waitcnt lgkmcnt(0)
	v_mfma_f32_16x16x32_bf16 v[126:129], v[140:143], v[204:207], v[126:129]
	v_mfma_f32_16x16x32_bf16 v[114:117], v[180:183], v[204:207], v[114:117]
	v_mfma_f32_16x16x32_bf16 v[106:109], v[140:143], v[212:215], v[106:109]
	v_mfma_f32_16x16x32_bf16 v[98:101], v[180:183], v[212:215], v[98:101]
	v_mfma_f32_16x16x32_bf16 v[90:93], v[140:143], v[220:223], v[90:93]
	v_mfma_f32_16x16x32_bf16 v[82:85], v[180:183], v[220:223], v[82:85]
	v_mfma_f32_16x16x32_bf16 v[74:77], v[140:143], v[228:231], v[74:77]
	v_mfma_f32_16x16x32_bf16 v[54:57], v[180:183], v[228:231], v[54:57]
	v_mfma_f32_16x16x32_bf16 v[126:129], v[176:179], v[208:211], v[126:129]
	v_mfma_f32_16x16x32_bf16 v[114:117], v[184:187], v[208:211], v[114:117]
	v_mfma_f32_16x16x32_bf16 v[106:109], v[176:179], v[216:219], v[106:109]
	v_mfma_f32_16x16x32_bf16 v[98:101], v[184:187], v[216:219], v[98:101]
	v_mfma_f32_16x16x32_bf16 v[90:93], v[176:179], v[224:227], v[90:93]
	v_mfma_f32_16x16x32_bf16 v[82:85], v[184:187], v[224:227], v[82:85]
	v_mfma_f32_16x16x32_bf16 v[74:77], v[176:179], v[232:235], v[74:77]
	v_mfma_f32_16x16x32_bf16 v[54:57], v[184:187], v[232:235], v[54:57]
	v_mfma_f32_16x16x32_bf16 v[118:121], v[188:191], v[204:207], v[118:121]
	v_mfma_f32_16x16x32_bf16 v[122:125], v[196:199], v[204:207], v[122:125]
	v_mfma_f32_16x16x32_bf16 v[102:105], v[188:191], v[212:215], v[102:105]
	v_mfma_f32_16x16x32_bf16 v[110:113], v[196:199], v[212:215], v[110:113]
	v_mfma_f32_16x16x32_bf16 v[86:89], v[188:191], v[220:223], v[86:89]
	v_mfma_f32_16x16x32_bf16 v[94:97], v[196:199], v[220:223], v[94:97]
	v_mfma_f32_16x16x32_bf16 v[70:73], v[188:191], v[228:231], v[70:73]
	v_mfma_f32_16x16x32_bf16 v[78:81], v[196:199], v[228:231], v[78:81]
	v_mfma_f32_16x16x32_bf16 v[118:121], v[192:195], v[208:211], v[118:121]
	v_mfma_f32_16x16x32_bf16 v[122:125], v[200:203], v[208:211], v[122:125]
	v_mfma_f32_16x16x32_bf16 v[102:105], v[192:195], v[216:219], v[102:105]
	v_mfma_f32_16x16x32_bf16 v[110:113], v[200:203], v[216:219], v[110:113]
	v_mfma_f32_16x16x32_bf16 v[86:89], v[192:195], v[224:227], v[86:89]
	v_mfma_f32_16x16x32_bf16 v[94:97], v[200:203], v[224:227], v[94:97]
	v_mfma_f32_16x16x32_bf16 v[70:73], v[192:195], v[232:235], v[70:73]
	v_mfma_f32_16x16x32_bf16 v[78:81], v[200:203], v[232:235], v[78:81]
	s_barrier
	s_add_i32 s30, s35, s23
	v_lshl_add_u64 v[144:145], v[144:145], 0, s[94:95]
	s_mov_b32 m0, s30
	ds_read_b128 v[204:207], v169 offset:49152
	ds_read_b128 v[208:211], v169 offset:50176
	ds_read_b128 v[212:215], v169 offset:51200
	ds_read_b128 v[216:219], v169 offset:52224
	ds_read_b128 v[220:223], v169 offset:53248
	ds_read_b128 v[224:227], v169 offset:54272
	ds_read_b128 v[228:231], v169 offset:55296
	ds_read_b128 v[232:235], v169 offset:56320
	global_load_lds_dwordx4 v[144:145], off
	v_lshl_add_u64 v[144:145], v[236:237], 0, s[94:95]
	s_add_i32 m0, s30, 0x2000
	s_add_i32 s30, s72, s23
	global_load_lds_dwordx4 v[144:145], off
	v_lshl_add_u64 v[144:145], v[238:239], 0, s[94:95]
	s_mov_b32 m0, s30
	s_nop 0
	global_load_lds_dwordx4 v[144:145], off
	v_lshl_add_u64 v[144:145], v[240:241], 0, s[94:95]
	s_add_i32 m0, s30, 0x2000
	s_nop 0
	global_load_lds_dwordx4 v[144:145], off
	v_lshl_add_u64 v[144:145], v[242:243], 0, s[94:95]
	s_mov_b32 m0, s64
	s_nop 0
	global_load_lds_dwordx4 v[144:145], off
	v_lshl_add_u64 v[144:145], v[244:245], 0, s[94:95]
	s_mov_b32 m0, s65
	s_nop 0
	global_load_lds_dwordx4 v[144:145], off
	s_waitcnt vmcnt(8)
	s_waitcnt lgkmcnt(0)
	s_barrier
	s_waitcnt lgkmcnt(0)
	v_mfma_f32_16x16x32_bf16 v[58:61], v[140:143], v[204:207], v[58:61]
	v_mfma_f32_16x16x32_bf16 v[62:65], v[180:183], v[204:207], v[62:65]
	v_mfma_f32_16x16x32_bf16 v[38:41], v[140:143], v[212:215], v[38:41]
	v_mfma_f32_16x16x32_bf16 v[42:45], v[180:183], v[212:215], v[42:45]
	v_mfma_f32_16x16x32_bf16 v[18:21], v[140:143], v[220:223], v[18:21]
	v_mfma_f32_16x16x32_bf16 v[26:29], v[180:183], v[220:223], v[26:29]
	v_mfma_f32_16x16x32_bf16 v[2:5], v[140:143], v[228:231], v[2:5]
	v_mfma_f32_16x16x32_bf16 v[6:9], v[180:183], v[228:231], v[6:9]
	v_mfma_f32_16x16x32_bf16 v[58:61], v[176:179], v[208:211], v[58:61]
	v_mfma_f32_16x16x32_bf16 v[62:65], v[184:187], v[208:211], v[62:65]
	v_mfma_f32_16x16x32_bf16 v[38:41], v[176:179], v[216:219], v[38:41]
	v_mfma_f32_16x16x32_bf16 v[42:45], v[184:187], v[216:219], v[42:45]
	v_mfma_f32_16x16x32_bf16 v[18:21], v[176:179], v[224:227], v[18:21]
	v_mfma_f32_16x16x32_bf16 v[26:29], v[184:187], v[224:227], v[26:29]
	v_mfma_f32_16x16x32_bf16 v[2:5], v[176:179], v[232:235], v[2:5]
	v_mfma_f32_16x16x32_bf16 v[6:9], v[184:187], v[232:235], v[6:9]
	v_mfma_f32_16x16x32_bf16 v[50:53], v[188:191], v[204:207], v[50:53]
	v_mfma_f32_16x16x32_bf16 v[66:69], v[196:199], v[204:207], v[66:69]
	v_mfma_f32_16x16x32_bf16 v[34:37], v[188:191], v[212:215], v[34:37]
	v_mfma_f32_16x16x32_bf16 v[46:49], v[196:199], v[212:215], v[46:49]
	v_mfma_f32_16x16x32_bf16 v[14:17], v[188:191], v[220:223], v[14:17]
	v_mfma_f32_16x16x32_bf16 v[30:33], v[196:199], v[220:223], v[30:33]
	v_mfma_f32_16x16x32_bf16 v[10:13], v[188:191], v[228:231], v[10:13]
	v_mfma_f32_16x16x32_bf16 v[22:25], v[196:199], v[228:231], v[22:25]
	v_mfma_f32_16x16x32_bf16 v[50:53], v[192:195], v[208:211], v[50:53]
	v_mfma_f32_16x16x32_bf16 v[66:69], v[200:203], v[208:211], v[66:69]
	v_mfma_f32_16x16x32_bf16 v[34:37], v[192:195], v[216:219], v[34:37]
	v_mfma_f32_16x16x32_bf16 v[46:49], v[200:203], v[216:219], v[46:49]
	v_mfma_f32_16x16x32_bf16 v[14:17], v[192:195], v[224:227], v[14:17]
	v_mfma_f32_16x16x32_bf16 v[30:33], v[200:203], v[224:227], v[30:33]
	v_mfma_f32_16x16x32_bf16 v[10:13], v[192:195], v[232:235], v[10:13]
	v_mfma_f32_16x16x32_bf16 v[22:25], v[200:203], v[232:235], v[22:25]
	s_barrier
	s_add_u32 s56, s56, 0x100
	s_addc_u32 s57, s57, 0
	s_add_u32 s18, s18, 0x100
	s_addc_u32 s19, s19, 0
	s_cmp_ge_u32 s29, s66
	s_mov_b32 s30, s29
	s_cbranch_scc0 .LBB0_290
	s_and_b64 vcc, exec, s[20:21]
	s_cbranch_vccz .LBB0_293
	s_barrier

.LBB0_311:
	s_or_b64 exec, exec, s[54:55]
	s_and_b64 vcc, exec, s[8:9]
	s_mov_b64 s[2:3], -1
	s_cbranch_vccnz .LBB0_281
	v_lshl_add_u32 v2, s17, 8, v146
	v_or_b32_e32 v8, 16, v2
	v_lshl_or_b32 v4, s16, 8, v168
	s_waitcnt lgkmcnt(0)
	v_ashrrev_i32_e32 v3, 31, v2
	v_ashrrev_i32_e32 v9, 31, v8
	v_ashrrev_i32_e32 v5, 31, v4
	v_lshlrev_b64 v[6:7], 11, v[2:3]
	v_lshlrev_b64 v[8:9], 11, v[8:9]
	v_lshl_add_u64 v[6:7], s[10:11], 0, v[6:7]
	v_lshlrev_b64 v[4:5], 1, v[4:5]
	v_lshl_add_u64 v[8:9], s[10:11], 0, v[8:9]
	v_lshl_add_u64 v[6:7], v[6:7], 0, v[4:5]
	v_lshl_add_u64 v[8:9], v[8:9], 0, v[4:5]
	global_load_dwordx4 v[62:65], v[6:7], off
	global_load_dwordx4 v[54:57], v[6:7], off offset:256
	global_load_dwordx4 v[58:61], v[8:9], off
	global_load_dwordx4 v[46:49], v[8:9], off offset:256
	v_or_b32_e32 v8, 32, v2
	v_or_b32_e32 v2, 48, v2
	v_ashrrev_i32_e32 v9, 31, v8
	v_ashrrev_i32_e32 v3, 31, v2
	v_lshlrev_b64 v[8:9], 11, v[8:9]
	v_lshlrev_b64 v[2:3], 11, v[2:3]
	v_lshl_add_u64 v[8:9], s[10:11], 0, v[8:9]
	v_lshl_add_u64 v[2:3], s[10:11], 0, v[2:3]
	s_mov_b32 s2, 0x40000
	v_lshl_add_u64 v[8:9], v[8:9], 0, v[4:5]
	v_lshl_add_u64 v[2:3], v[2:3], 0, v[4:5]
	v_add_co_u32_e32 v4, vcc, s2, v6
	s_mov_b32 s2, 0x48000
	s_nop 0
	v_addc_co_u32_e32 v5, vcc, 0, v7, vcc
	global_load_dwordx4 v[50:53], v[8:9], off
	global_load_dwordx4 v[38:41], v[8:9], off offset:256
	global_load_dwordx4 v[42:45], v[2:3], off
	global_load_dwordx4 v[30:33], v[2:3], off offset:256
	v_lshl_add_u64 v[2:3], v[6:7], 0, s[90:91]
	global_load_dwordx4 v[34:37], v[4:5], off
	global_load_dwordx4 v[18:21], v[2:3], off offset:256
	v_add_co_u32_e32 v4, vcc, s2, v6
	v_lshl_add_u64 v[2:3], v[6:7], 0, s[92:93]
	s_nop 0
	v_addc_co_u32_e32 v5, vcc, 0, v7, vcc
	global_load_dwordx4 v[26:29], v[4:5], off
	global_load_dwordx4 v[10:13], v[2:3], off offset:256
	v_add_co_u32_e32 v4, vcc, 0x50000, v6
	s_mov_b64 s[2:3], 0x58000
	s_nop 0
	v_addc_co_u32_e32 v5, vcc, 0, v7, vcc
	v_lshl_add_u64 v[2:3], v[6:7], 0, s[98:99]
	v_lshl_add_u64 v[22:23], v[6:7], 0, s[2:3]
	v_add_co_u32_e32 v6, vcc, 0x58000, v6
	global_load_dwordx4 v[14:17], v[4:5], off
	s_nop 0
	global_load_dwordx4 v[2:5], v[2:3], off offset:256
	v_addc_co_u32_e32 v7, vcc, 0, v7, vcc
	global_load_dwordx4 v[6:9], v[6:7], off
	s_nop 0
	global_load_dwordx4 v[22:25], v[22:23], off offset:256
	v_readlane_b32 s2, v248, 29
	v_readlane_b32 s3, v248, 30
	s_andn2_b64 vcc, exec, s[2:3]
	s_cbranch_vccnz .LBB0_280
	s_mov_b32 s100, 1
	s_branch .LBB0_280

.LBB0_333:
	s_add_u32 s16, s16, 0x80
	s_addc_u32 s17, s17, 0
	s_add_u32 s64, s20, 0x100
	v_mov_b32_e32 v2, 0
	s_addc_u32 s65, s21, 0
	s_mov_b32 s20, 0
	v_mov_b32_e32 v3, v2
	v_mov_b32_e32 v4, v2
	v_mov_b32_e32 v5, v2
	v_mov_b32_e32 v6, v2
	v_mov_b32_e32 v7, v2
	v_mov_b32_e32 v8, v2
	v_mov_b32_e32 v9, v2
	v_mov_b32_e32 v18, v2
	v_mov_b32_e32 v19, v2
	v_mov_b32_e32 v20, v2
	v_mov_b32_e32 v21, v2
	v_mov_b32_e32 v22, v2
	v_mov_b32_e32 v23, v2
	v_mov_b32_e32 v24, v2
	v_mov_b32_e32 v25, v2
	v_mov_b32_e32 v34, v2
	v_mov_b32_e32 v35, v2
	v_mov_b32_e32 v36, v2
	v_mov_b32_e32 v37, v2
	v_mov_b32_e32 v38, v2
	v_mov_b32_e32 v39, v2
	v_mov_b32_e32 v40, v2
	v_mov_b32_e32 v41, v2
	v_mov_b32_e32 v50, v2
	v_mov_b32_e32 v51, v2
	v_mov_b32_e32 v52, v2
	v_mov_b32_e32 v53, v2
	v_mov_b32_e32 v54, v2
	v_mov_b32_e32 v55, v2
	v_mov_b32_e32 v56, v2
	v_mov_b32_e32 v57, v2
	v_mov_b32_e32 v10, v2
	v_mov_b32_e32 v11, v2
	v_mov_b32_e32 v12, v2
	v_mov_b32_e32 v13, v2
	v_mov_b32_e32 v14, v2
	v_mov_b32_e32 v15, v2
	v_mov_b32_e32 v16, v2
	v_mov_b32_e32 v17, v2
	v_mov_b32_e32 v26, v2
	v_mov_b32_e32 v27, v2
	v_mov_b32_e32 v28, v2
	v_mov_b32_e32 v29, v2
	v_mov_b32_e32 v30, v2
	v_mov_b32_e32 v31, v2
	v_mov_b32_e32 v32, v2
	v_mov_b32_e32 v33, v2
	v_mov_b32_e32 v42, v2
	v_mov_b32_e32 v43, v2
	v_mov_b32_e32 v44, v2
	v_mov_b32_e32 v45, v2
	v_mov_b32_e32 v46, v2
	v_mov_b32_e32 v47, v2
	v_mov_b32_e32 v48, v2
	v_mov_b32_e32 v49, v2
	v_mov_b32_e32 v58, v2
	v_mov_b32_e32 v59, v2
	v_mov_b32_e32 v60, v2
	v_mov_b32_e32 v61, v2
	v_mov_b32_e32 v62, v2
	v_mov_b32_e32 v63, v2
	v_mov_b32_e32 v64, v2
	v_mov_b32_e32 v65, v2
	v_mov_b32_e32 v66, v2
	v_mov_b32_e32 v67, v2
	v_mov_b32_e32 v68, v2
	v_mov_b32_e32 v69, v2
	v_mov_b32_e32 v70, v2
	v_mov_b32_e32 v71, v2
	v_mov_b32_e32 v72, v2
	v_mov_b32_e32 v73, v2
	v_mov_b32_e32 v82, v2
	v_mov_b32_e32 v83, v2
	v_mov_b32_e32 v84, v2
	v_mov_b32_e32 v85, v2
	v_mov_b32_e32 v86, v2
	v_mov_b32_e32 v87, v2
	v_mov_b32_e32 v88, v2
	v_mov_b32_e32 v89, v2
	v_mov_b32_e32 v98, v2
	v_mov_b32_e32 v99, v2
	v_mov_b32_e32 v100, v2
	v_mov_b32_e32 v101, v2
	v_mov_b32_e32 v102, v2
	v_mov_b32_e32 v103, v2
	v_mov_b32_e32 v104, v2
	v_mov_b32_e32 v105, v2
	v_mov_b32_e32 v114, v2
	v_mov_b32_e32 v115, v2
	v_mov_b32_e32 v116, v2
	v_mov_b32_e32 v117, v2
	v_mov_b32_e32 v118, v2
	v_mov_b32_e32 v119, v2
	v_mov_b32_e32 v120, v2
	v_mov_b32_e32 v121, v2
	v_mov_b32_e32 v74, v2
	v_mov_b32_e32 v75, v2
	v_mov_b32_e32 v76, v2
	v_mov_b32_e32 v77, v2
	v_mov_b32_e32 v78, v2
	v_mov_b32_e32 v79, v2
	v_mov_b32_e32 v80, v2
	v_mov_b32_e32 v81, v2
	v_mov_b32_e32 v90, v2
	v_mov_b32_e32 v91, v2
	v_mov_b32_e32 v92, v2
	v_mov_b32_e32 v93, v2
	v_mov_b32_e32 v94, v2
	v_mov_b32_e32 v95, v2
	v_mov_b32_e32 v96, v2
	v_mov_b32_e32 v97, v2
	v_mov_b32_e32 v106, v2
	v_mov_b32_e32 v107, v2
	v_mov_b32_e32 v108, v2
	v_mov_b32_e32 v109, v2
	v_mov_b32_e32 v110, v2
	v_mov_b32_e32 v111, v2
	v_mov_b32_e32 v112, v2
	v_mov_b32_e32 v113, v2
	v_mov_b32_e32 v122, v2
	v_mov_b32_e32 v123, v2
	v_mov_b32_e32 v124, v2
	v_mov_b32_e32 v125, v2
	v_mov_b32_e32 v126, v2
	v_mov_b32_e32 v127, v2
	v_mov_b32_e32 v128, v2
	v_mov_b32_e32 v129, v2
	s_cmp_eq_u32 s100, 1
	s_cbranch_scc0 .Ldb_334
	s_mov_b32 s100, 0
	s_barrier
.Ldb_334:
.LBB0_334:
	s_add_i32 s66, s20, 2
	s_add_u32 s67, s16, 0x80
	s_addc_u32 s21, s17, 0
	s_add_i32 s72, 0, 0x10000
	s_cmp_eq_u32 s58, s20
	s_cselect_b32 s21, s1, s21
	s_cselect_b32 s20, s0, s67
	v_add_u32_e32 v140, s72, v143
	s_cselect_b32 s71, s15, s65
	s_cselect_b32 s70, s14, s64
	s_add_i32 s67, 0, 0x14000
	ds_read_b128 v[160:163], v140
	ds_read_b128 v[164:167], v140 offset:1024
	ds_read_b128 v[168:171], v140 offset:2048
	ds_read_b128 v[172:175], v140 offset:3072
	v_add_u32_e32 v140, s67, v143
	ds_read_b128 v[176:179], v140
	ds_read_b128 v[180:183], v140 offset:1024
	ds_read_b128 v[184:187], v140 offset:2048
	ds_read_b128 v[188:191], v140 offset:3072
	v_lshl_add_u64 v[140:141], s[16:17], 0, v[136:137]
	s_add_i32 m0, s19, 0xc000
	ds_read_b128 v[192:195], v146
	ds_read_b128 v[196:199], v146 offset:1024
	ds_read_b128 v[200:203], v146 offset:2048
	ds_read_b128 v[204:207], v146 offset:3072
	ds_read_b128 v[208:211], v146 offset:4096
	ds_read_b128 v[212:215], v146 offset:5120
	ds_read_b128 v[216:219], v146 offset:6144
	ds_read_b128 v[220:223], v146 offset:7168
	global_load_lds_dwordx4 v[140:141], off
	v_lshl_add_u64 v[140:141], s[16:17], 0, v[138:139]
	s_add_i32 m0, s19, 0xe000
	s_nop 0
	global_load_lds_dwordx4 v[140:141], off
	s_waitcnt vmcnt(8)
	s_waitcnt lgkmcnt(0)
	s_barrier
	s_waitcnt lgkmcnt(0)
	v_mfma_f32_16x16x32_bf16 v[126:129], v[160:163], v[192:195], v[126:129]
	v_mfma_f32_16x16x32_bf16 v[122:125], v[168:171], v[192:195], v[122:125]
	v_mfma_f32_16x16x32_bf16 v[110:113], v[160:163], v[200:203], v[110:113]
	v_mfma_f32_16x16x32_bf16 v[106:109], v[168:171], v[200:203], v[106:109]
	v_mfma_f32_16x16x32_bf16 v[94:97], v[160:163], v[208:211], v[94:97]
	v_mfma_f32_16x16x32_bf16 v[90:93], v[168:171], v[208:211], v[90:93]
	v_mfma_f32_16x16x32_bf16 v[78:81], v[160:163], v[216:219], v[78:81]
	v_mfma_f32_16x16x32_bf16 v[74:77], v[168:171], v[216:219], v[74:77]
	v_mfma_f32_16x16x32_bf16 v[126:129], v[164:167], v[196:199], v[126:129]
	v_mfma_f32_16x16x32_bf16 v[122:125], v[172:175], v[196:199], v[122:125]
	v_mfma_f32_16x16x32_bf16 v[110:113], v[164:167], v[204:207], v[110:113]
	v_mfma_f32_16x16x32_bf16 v[106:109], v[172:175], v[204:207], v[106:109]
	v_mfma_f32_16x16x32_bf16 v[94:97], v[164:167], v[212:215], v[94:97]
	v_mfma_f32_16x16x32_bf16 v[90:93], v[172:175], v[212:215], v[90:93]
	v_mfma_f32_16x16x32_bf16 v[78:81], v[164:167], v[220:223], v[78:81]
	v_mfma_f32_16x16x32_bf16 v[74:77], v[172:175], v[220:223], v[74:77]
	v_mfma_f32_16x16x32_bf16 v[118:121], v[176:179], v[192:195], v[118:121]
	v_mfma_f32_16x16x32_bf16 v[114:117], v[184:187], v[192:195], v[114:117]
	v_mfma_f32_16x16x32_bf16 v[102:105], v[176:179], v[200:203], v[102:105]
	v_mfma_f32_16x16x32_bf16 v[98:101], v[184:187], v[200:203], v[98:101]
	v_mfma_f32_16x16x32_bf16 v[86:89], v[176:179], v[208:211], v[86:89]
	v_mfma_f32_16x16x32_bf16 v[82:85], v[184:187], v[208:211], v[82:85]
	v_mfma_f32_16x16x32_bf16 v[70:73], v[176:179], v[216:219], v[70:73]
	v_mfma_f32_16x16x32_bf16 v[66:69], v[184:187], v[216:219], v[66:69]
	v_mfma_f32_16x16x32_bf16 v[118:121], v[180:183], v[196:199], v[118:121]
	v_mfma_f32_16x16x32_bf16 v[114:117], v[188:191], v[196:199], v[114:117]
	v_mfma_f32_16x16x32_bf16 v[102:105], v[180:183], v[204:207], v[102:105]
	v_mfma_f32_16x16x32_bf16 v[98:101], v[188:191], v[204:207], v[98:101]
	v_mfma_f32_16x16x32_bf16 v[86:89], v[180:183], v[212:215], v[86:89]
	v_mfma_f32_16x16x32_bf16 v[82:85], v[188:191], v[212:215], v[82:85]
	v_mfma_f32_16x16x32_bf16 v[70:73], v[180:183], v[220:223], v[70:73]
	v_mfma_f32_16x16x32_bf16 v[66:69], v[188:191], v[220:223], v[66:69]
	s_barrier
	s_add_i32 s72, s72, s35
	v_lshl_add_u64 v[140:141], s[70:71], 0, v[0:1]
	s_mov_b32 m0, s72
	ds_read_b128 v[192:195], v146 offset:16384
	ds_read_b128 v[196:199], v146 offset:17408
	ds_read_b128 v[200:203], v146 offset:18432
	ds_read_b128 v[204:207], v146 offset:19456
	ds_read_b128 v[208:211], v146 offset:20480
	ds_read_b128 v[212:215], v146 offset:21504
	ds_read_b128 v[216:219], v146 offset:22528
	ds_read_b128 v[220:223], v146 offset:23552
	global_load_lds_dwordx4 v[140:141], off
	s_add_i32 m0, s72, 0x2000
	v_lshl_add_u64 v[148:149], s[70:71], 0, v[134:135]
	s_add_u32 s70, s70, s80
	s_addc_u32 s71, s71, 0
	s_add_i32 s67, s67, s35
	global_load_lds_dwordx4 v[148:149], off
	v_lshl_add_u64 v[224:225], s[70:71], 0, v[0:1]
	s_mov_b32 m0, s67
	v_lshl_add_u64 v[226:227], s[70:71], 0, v[134:135]
	global_load_lds_dwordx4 v[224:225], off
	s_add_i32 m0, s67, 0x2000
	v_lshl_add_u64 v[228:229], s[20:21], 0, v[130:131]
	global_load_lds_dwordx4 v[226:227], off
	s_mov_b32 m0, s19
	v_lshl_add_u64 v[230:231], s[20:21], 0, v[132:133]
	global_load_lds_dwordx4 v[228:229], off
	s_mov_b32 m0, s29
	s_nop 0
	global_load_lds_dwordx4 v[230:231], off
	s_waitcnt vmcnt(8)
	s_waitcnt lgkmcnt(0)
	s_barrier
	s_waitcnt lgkmcnt(0)
	v_mfma_f32_16x16x32_bf16 v[62:65], v[160:163], v[192:195], v[62:65]
	v_mfma_f32_16x16x32_bf16 v[58:61], v[168:171], v[192:195], v[58:61]
	v_mfma_f32_16x16x32_bf16 v[46:49], v[160:163], v[200:203], v[46:49]
	v_mfma_f32_16x16x32_bf16 v[42:45], v[168:171], v[200:203], v[42:45]
	v_mfma_f32_16x16x32_bf16 v[30:33], v[160:163], v[208:211], v[30:33]
	v_mfma_f32_16x16x32_bf16 v[26:29], v[168:171], v[208:211], v[26:29]
	v_mfma_f32_16x16x32_bf16 v[14:17], v[160:163], v[216:219], v[14:17]
	v_mfma_f32_16x16x32_bf16 v[10:13], v[168:171], v[216:219], v[10:13]
	v_mfma_f32_16x16x32_bf16 v[62:65], v[164:167], v[196:199], v[62:65]
	v_mfma_f32_16x16x32_bf16 v[58:61], v[172:175], v[196:199], v[58:61]
	v_mfma_f32_16x16x32_bf16 v[46:49], v[164:167], v[204:207], v[46:49]
	v_mfma_f32_16x16x32_bf16 v[42:45], v[172:175], v[204:207], v[42:45]
	v_mfma_f32_16x16x32_bf16 v[30:33], v[164:167], v[212:215], v[30:33]
	v_mfma_f32_16x16x32_bf16 v[26:29], v[172:175], v[212:215], v[26:29]
	v_mfma_f32_16x16x32_bf16 v[14:17], v[164:167], v[220:223], v[14:17]
	v_mfma_f32_16x16x32_bf16 v[10:13], v[172:175], v[220:223], v[10:13]
	v_mfma_f32_16x16x32_bf16 v[54:57], v[176:179], v[192:195], v[54:57]
	v_mfma_f32_16x16x32_bf16 v[50:53], v[184:187], v[192:195], v[50:53]
	v_mfma_f32_16x16x32_bf16 v[38:41], v[176:179], v[200:203], v[38:41]
	v_mfma_f32_16x16x32_bf16 v[34:37], v[184:187], v[200:203], v[34:37]
	v_mfma_f32_16x16x32_bf16 v[22:25], v[176:179], v[208:211], v[22:25]
	v_mfma_f32_16x16x32_bf16 v[18:21], v[184:187], v[208:211], v[18:21]
	v_mfma_f32_16x16x32_bf16 v[6:9], v[176:179], v[216:219], v[6:9]
	v_mfma_f32_16x16x32_bf16 v[2:5], v[184:187], v[216:219], v[2:5]
	v_mfma_f32_16x16x32_bf16 v[54:57], v[180:183], v[196:199], v[54:57]
	v_mfma_f32_16x16x32_bf16 v[50:53], v[188:191], v[196:199], v[50:53]
	v_mfma_f32_16x16x32_bf16 v[38:41], v[180:183], v[204:207], v[38:41]
	v_mfma_f32_16x16x32_bf16 v[34:37], v[188:191], v[204:207], v[34:37]
	v_mfma_f32_16x16x32_bf16 v[22:25], v[180:183], v[212:215], v[22:25]
	v_mfma_f32_16x16x32_bf16 v[18:21], v[188:191], v[212:215], v[18:21]
	v_mfma_f32_16x16x32_bf16 v[6:9], v[180:183], v[220:223], v[6:9]
	v_mfma_f32_16x16x32_bf16 v[2:5], v[188:191], v[220:223], v[2:5]
	s_barrier
	s_add_i32 s67, 0, 0x18000
	v_add_u32_e32 v159, s67, v143
	s_add_i32 s70, 0, 0x1c000
	ds_read_b128 v[160:163], v159
	ds_read_b128 v[164:167], v159 offset:1024
	ds_read_b128 v[168:171], v159 offset:2048
	ds_read_b128 v[172:175], v159 offset:3072
	v_add_u32_e32 v159, s70, v143
	ds_read_b128 v[176:179], v159
	ds_read_b128 v[180:183], v159 offset:1024
	ds_read_b128 v[184:187], v159 offset:2048
	ds_read_b128 v[188:191], v159 offset:3072
	s_add_u32 s20, s20, s80
	s_addc_u32 s21, s21, 0
	s_mov_b32 m0, s30
	v_lshl_add_u64 v[232:233], s[20:21], 0, v[130:131]
	ds_read_b128 v[192:195], v146 offset:32768
	ds_read_b128 v[196:199], v146 offset:33792
	ds_read_b128 v[200:203], v146 offset:34816
	ds_read_b128 v[204:207], v146 offset:35840
	ds_read_b128 v[208:211], v146 offset:36864
	ds_read_b128 v[212:215], v146 offset:37888
	ds_read_b128 v[216:219], v146 offset:38912
	ds_read_b128 v[220:223], v146 offset:39936
	global_load_lds_dwordx4 v[232:233], off
	v_lshl_add_u64 v[232:233], s[20:21], 0, v[132:133]
	s_mov_b32 m0, s31
	s_nop 0
	global_load_lds_dwordx4 v[232:233], off
	s_waitcnt vmcnt(8)
	s_waitcnt lgkmcnt(0)
	s_barrier
	s_waitcnt lgkmcnt(0)
	v_mfma_f32_16x16x32_bf16 v[126:129], v[160:163], v[192:195], v[126:129]
	v_mfma_f32_16x16x32_bf16 v[122:125], v[168:171], v[192:195], v[122:125]
	v_mfma_f32_16x16x32_bf16 v[110:113], v[160:163], v[200:203], v[110:113]
	v_mfma_f32_16x16x32_bf16 v[106:109], v[168:171], v[200:203], v[106:109]
	v_mfma_f32_16x16x32_bf16 v[94:97], v[160:163], v[208:211], v[94:97]
	v_mfma_f32_16x16x32_bf16 v[90:93], v[168:171], v[208:211], v[90:93]
	v_mfma_f32_16x16x32_bf16 v[78:81], v[160:163], v[216:219], v[78:81]
	v_mfma_f32_16x16x32_bf16 v[74:77], v[168:171], v[216:219], v[74:77]
	v_mfma_f32_16x16x32_bf16 v[126:129], v[164:167], v[196:199], v[126:129]
	v_mfma_f32_16x16x32_bf16 v[122:125], v[172:175], v[196:199], v[122:125]
	v_mfma_f32_16x16x32_bf16 v[110:113], v[164:167], v[204:207], v[110:113]
	v_mfma_f32_16x16x32_bf16 v[106:109], v[172:175], v[204:207], v[106:109]
	v_mfma_f32_16x16x32_bf16 v[94:97], v[164:167], v[212:215], v[94:97]
	v_mfma_f32_16x16x32_bf16 v[90:93], v[172:175], v[212:215], v[90:93]
	v_mfma_f32_16x16x32_bf16 v[78:81], v[164:167], v[220:223], v[78:81]
	v_mfma_f32_16x16x32_bf16 v[74:77], v[172:175], v[220:223], v[74:77]
	v_mfma_f32_16x16x32_bf16 v[118:121], v[176:179], v[192:195], v[118:121]
	v_mfma_f32_16x16x32_bf16 v[114:117], v[184:187], v[192:195], v[114:117]
	v_mfma_f32_16x16x32_bf16 v[102:105], v[176:179], v[200:203], v[102:105]
	v_mfma_f32_16x16x32_bf16 v[98:101], v[184:187], v[200:203], v[98:101]
	v_mfma_f32_16x16x32_bf16 v[86:89], v[176:179], v[208:211], v[86:89]
	v_mfma_f32_16x16x32_bf16 v[82:85], v[184:187], v[208:211], v[82:85]
	v_mfma_f32_16x16x32_bf16 v[70:73], v[176:179], v[216:219], v[70:73]
	v_mfma_f32_16x16x32_bf16 v[66:69], v[184:187], v[216:219], v[66:69]
	v_mfma_f32_16x16x32_bf16 v[118:121], v[180:183], v[196:199], v[118:121]
	v_mfma_f32_16x16x32_bf16 v[114:117], v[188:191], v[196:199], v[114:117]
	v_mfma_f32_16x16x32_bf16 v[102:105], v[180:183], v[204:207], v[102:105]
	v_mfma_f32_16x16x32_bf16 v[98:101], v[188:191], v[204:207], v[98:101]
	v_mfma_f32_16x16x32_bf16 v[86:89], v[180:183], v[212:215], v[86:89]
	v_mfma_f32_16x16x32_bf16 v[82:85], v[188:191], v[212:215], v[82:85]
	v_mfma_f32_16x16x32_bf16 v[70:73], v[180:183], v[220:223], v[70:73]
	v_mfma_f32_16x16x32_bf16 v[66:69], v[188:191], v[220:223], v[66:69]
	s_barrier
	s_add_i32 s20, s67, s35
	v_lshl_add_u64 v[140:141], v[140:141], 0, s[94:95]
	s_mov_b32 m0, s20
	ds_read_b128 v[192:195], v146 offset:49152
	ds_read_b128 v[196:199], v146 offset:50176
	ds_read_b128 v[200:203], v146 offset:51200
	ds_read_b128 v[204:207], v146 offset:52224
	ds_read_b128 v[208:211], v146 offset:53248
	ds_read_b128 v[212:215], v146 offset:54272
	ds_read_b128 v[216:219], v146 offset:55296
	ds_read_b128 v[220:223], v146 offset:56320
	global_load_lds_dwordx4 v[140:141], off
	v_lshl_add_u64 v[140:141], v[148:149], 0, s[94:95]
	s_add_i32 m0, s20, 0x2000
	s_add_i32 s20, s70, s35
	global_load_lds_dwordx4 v[140:141], off
	v_lshl_add_u64 v[140:141], v[224:225], 0, s[94:95]
	s_mov_b32 m0, s20
	s_nop 0
	global_load_lds_dwordx4 v[140:141], off
	v_lshl_add_u64 v[140:141], v[226:227], 0, s[94:95]
	s_add_i32 m0, s20, 0x2000
	s_nop 0
	global_load_lds_dwordx4 v[140:141], off
	v_lshl_add_u64 v[140:141], v[228:229], 0, s[94:95]
	s_mov_b32 m0, s56
	s_nop 0
	global_load_lds_dwordx4 v[140:141], off
	v_lshl_add_u64 v[140:141], v[230:231], 0, s[94:95]
	s_mov_b32 m0, s57
	s_nop 0
	global_load_lds_dwordx4 v[140:141], off
	s_waitcnt vmcnt(8)
	s_waitcnt lgkmcnt(0)
	s_barrier
	s_waitcnt lgkmcnt(0)
	v_mfma_f32_16x16x32_bf16 v[62:65], v[160:163], v[192:195], v[62:65]
	v_mfma_f32_16x16x32_bf16 v[58:61], v[168:171], v[192:195], v[58:61]
	v_mfma_f32_16x16x32_bf16 v[46:49], v[160:163], v[200:203], v[46:49]
	v_mfma_f32_16x16x32_bf16 v[42:45], v[168:171], v[200:203], v[42:45]
	v_mfma_f32_16x16x32_bf16 v[30:33], v[160:163], v[208:211], v[30:33]
	v_mfma_f32_16x16x32_bf16 v[26:29], v[168:171], v[208:211], v[26:29]
	v_mfma_f32_16x16x32_bf16 v[14:17], v[160:163], v[216:219], v[14:17]
	v_mfma_f32_16x16x32_bf16 v[10:13], v[168:171], v[216:219], v[10:13]
	v_mfma_f32_16x16x32_bf16 v[62:65], v[164:167], v[196:199], v[62:65]
	v_mfma_f32_16x16x32_bf16 v[58:61], v[172:175], v[196:199], v[58:61]
	v_mfma_f32_16x16x32_bf16 v[46:49], v[164:167], v[204:207], v[46:49]
	v_mfma_f32_16x16x32_bf16 v[42:45], v[172:175], v[204:207], v[42:45]
	v_mfma_f32_16x16x32_bf16 v[30:33], v[164:167], v[212:215], v[30:33]
	v_mfma_f32_16x16x32_bf16 v[26:29], v[172:175], v[212:215], v[26:29]
	v_mfma_f32_16x16x32_bf16 v[14:17], v[164:167], v[220:223], v[14:17]
	v_mfma_f32_16x16x32_bf16 v[10:13], v[172:175], v[220:223], v[10:13]
	v_mfma_f32_16x16x32_bf16 v[54:57], v[176:179], v[192:195], v[54:57]
	v_mfma_f32_16x16x32_bf16 v[50:53], v[184:187], v[192:195], v[50:53]
	v_mfma_f32_16x16x32_bf16 v[38:41], v[176:179], v[200:203], v[38:41]
	v_mfma_f32_16x16x32_bf16 v[34:37], v[184:187], v[200:203], v[34:37]
	v_mfma_f32_16x16x32_bf16 v[22:25], v[176:179], v[208:211], v[22:25]
	v_mfma_f32_16x16x32_bf16 v[18:21], v[184:187], v[208:211], v[18:21]
	v_mfma_f32_16x16x32_bf16 v[6:9], v[176:179], v[216:219], v[6:9]
	v_mfma_f32_16x16x32_bf16 v[2:5], v[184:187], v[216:219], v[2:5]
	v_mfma_f32_16x16x32_bf16 v[54:57], v[180:183], v[196:199], v[54:57]
	v_mfma_f32_16x16x32_bf16 v[50:53], v[188:191], v[196:199], v[50:53]
	v_mfma_f32_16x16x32_bf16 v[38:41], v[180:183], v[204:207], v[38:41]
	v_mfma_f32_16x16x32_bf16 v[34:37], v[188:191], v[204:207], v[34:37]
	v_mfma_f32_16x16x32_bf16 v[22:25], v[180:183], v[212:215], v[22:25]
	v_mfma_f32_16x16x32_bf16 v[18:21], v[188:191], v[212:215], v[18:21]
	v_mfma_f32_16x16x32_bf16 v[6:9], v[180:183], v[220:223], v[6:9]
	v_mfma_f32_16x16x32_bf16 v[2:5], v[188:191], v[220:223], v[2:5]
	s_barrier
	s_add_u32 s16, s16, 0x100
	s_addc_u32 s17, s17, 0
	s_add_u32 s64, s64, 0x100
	s_addc_u32 s65, s65, 0
	s_cmp_ge_u32 s66, s55
	s_mov_b32 s20, s66
	s_cbranch_scc0 .LBB0_334
	s_and_b64 vcc, exec, s[10:11]
	s_cbranch_vccz .LBB0_337
	s_barrier
.LBB0_337:
	ds_read_b128 v[160:163], v147
	v_lshl_add_u32 v148, s62, 8, v142
	v_ashrrev_i32_e32 v149, 31, v148
	v_mul_lo_u32 v149, s68, v149
	v_mul_lo_u32 v159, s69, v148
	s_waitcnt lgkmcnt(0)
	v_mov_b32_e32 v166, v161
	v_mov_b32_e32 v167, v162
	v_mov_b32_e32 v161, v163
	v_mad_u64_u32 v[164:165], s[16:17], s68, v148, 0
	v_pk_add_f32 v[160:161], v[166:167], v[160:161]
	v_add3_u32 v165, v165, v149, v159
	v_add_f32_e32 v159, v160, v161
	v_fmamk_f32 v159, v159, 0x3a800000, v155
	v_rsq_f32_e32 v159, v159
	v_lshl_add_u64 v[160:161], v[164:165], 1, s[78:79]
	v_lshl_or_b32 v140, s63, 8, v144
	v_ashrrev_i32_e32 v141, 31, v140
	v_mul_f32_e32 v162, v159, v159
	v_max_f32_e32 v165, 0, v129
	v_max_f32_e32 v164, 0, v128
	v_max_f32_e32 v167, 0, v127
	v_max_f32_e32 v166, 0, v126
	v_pk_mul_f32 v[128:129], v[128:129], v[164:165]
	v_max_f32_e32 v165, 0, v125
	v_max_f32_e32 v164, 0, v124
	v_pk_mul_f32 v[126:127], v[126:127], v[166:167]
	v_max_f32_e32 v167, 0, v123
	v_max_f32_e32 v166, 0, v122
	v_pk_mul_f32 v[122:123], v[122:123], v[166:167]
	v_pk_mul_f32 v[124:125], v[124:125], v[164:165]
	v_lshlrev_b64 v[140:141], 1, v[140:141]
	v_pk_mul_f32 v[164:165], v[124:125], v[162:163] op_sel_hi:[1,0]
	v_pk_mul_f32 v[124:125], v[122:123], v[162:163] op_sel_hi:[1,0]
	v_lshl_add_u64 v[160:161], v[160:161], 0, v[140:141]
	v_pk_mul_f32 v[128:129], v[128:129], v[162:163] op_sel_hi:[1,0]
	v_pk_mul_f32 v[126:127], v[126:127], v[162:163] op_sel_hi:[1,0]
	s_and_b64 vcc, exec, s[6:7]
	v_cvt_pk_bf16_f32 v122, v126, v127
	v_cvt_pk_bf16_f32 v123, v128, v129
	v_cvt_pk_bf16_f32 v124, v124, v125
	v_cvt_pk_bf16_f32 v125, v164, v165
	global_store_dwordx4 v[160:161], v[122:125], off
	s_mov_b64 s[6:7], -1
	s_nop 0
	v_max_f32_e32 v123, 0, v121
	v_max_f32_e32 v125, 0, v119
	v_max_f32_e32 v122, 0, v120
	v_max_f32_e32 v124, 0, v118
	v_pk_mul_f32 v[118:119], v[118:119], v[124:125]
	v_pk_mul_f32 v[120:121], v[120:121], v[122:123]
	v_max_f32_e32 v123, 0, v117
	v_max_f32_e32 v125, 0, v115
	v_max_f32_e32 v122, 0, v116
	v_max_f32_e32 v124, 0, v114
	v_pk_mul_f32 v[114:115], v[114:115], v[124:125]
	v_pk_mul_f32 v[116:117], v[116:117], v[122:123]
	v_pk_mul_f32 v[120:121], v[120:121], v[162:163] op_sel_hi:[1,0]
	v_pk_mul_f32 v[122:123], v[116:117], v[162:163] op_sel_hi:[1,0]
	v_pk_mul_f32 v[116:117], v[114:115], v[162:163] op_sel_hi:[1,0]
	v_pk_mul_f32 v[118:119], v[118:119], v[162:163] op_sel_hi:[1,0]
	s_nop 0
	v_cvt_pk_bf16_f32 v114, v118, v119
	v_cvt_pk_bf16_f32 v115, v120, v121
	v_cvt_pk_bf16_f32 v116, v116, v117
	v_cvt_pk_bf16_f32 v117, v122, v123
	global_store_dwordx4 v[160:161], v[114:117], off offset:256
	ds_read_b128 v[114:117], v147 offset:256
	v_or_b32_e32 v118, 16, v148
	v_mul_lo_u32 v122, s69, v118
	v_mad_u64_u32 v[118:119], s[16:17], s68, v118, 0
	s_waitcnt lgkmcnt(0)
	v_mov_b32_e32 v120, v115
	v_mov_b32_e32 v121, v116
	v_mov_b32_e32 v115, v117
	v_pk_add_f32 v[114:115], v[120:121], v[114:115]
	v_add3_u32 v119, v119, v149, v122
	v_add_f32_e32 v114, v114, v115
	v_fmamk_f32 v114, v114, 0x3a800000, v155
	v_rsq_f32_e32 v116, v114
	v_lshl_add_u64 v[114:115], v[118:119], 1, s[78:79]
	v_max_f32_e32 v119, 0, v113
	v_max_f32_e32 v118, 0, v112
	v_max_f32_e32 v121, 0, v111
	v_max_f32_e32 v120, 0, v110
	v_mul_f32_e32 v116, v116, v116
	v_pk_mul_f32 v[110:111], v[110:111], v[120:121]
	v_pk_mul_f32 v[112:113], v[112:113], v[118:119]
	v_pk_mul_f32 v[110:111], v[110:111], v[116:117] op_sel_hi:[1,0]
	v_pk_mul_f32 v[112:113], v[112:113], v[116:117] op_sel_hi:[1,0]
	v_max_f32_e32 v119, 0, v109
	v_max_f32_e32 v118, 0, v108
	v_max_f32_e32 v121, 0, v107
	v_max_f32_e32 v120, 0, v106
	v_pk_mul_f32 v[106:107], v[106:107], v[120:121]
	v_pk_mul_f32 v[108:109], v[108:109], v[118:119]
	v_lshl_add_u64 v[114:115], v[114:115], 0, v[140:141]
	v_pk_mul_f32 v[118:119], v[108:109], v[116:117] op_sel_hi:[1,0]
	v_pk_mul_f32 v[108:109], v[106:107], v[116:117] op_sel_hi:[1,0]
	v_cvt_pk_bf16_f32 v106, v110, v111
	v_cvt_pk_bf16_f32 v107, v112, v113
	s_nop 0
	v_cvt_pk_bf16_f32 v108, v108, v109
	v_cvt_pk_bf16_f32 v109, v118, v119
	global_store_dwordx4 v[114:115], v[106:109], off
	s_nop 1
	v_max_f32_e32 v107, 0, v105
	v_max_f32_e32 v109, 0, v103
	v_max_f32_e32 v106, 0, v104
	v_max_f32_e32 v108, 0, v102
	v_pk_mul_f32 v[102:103], v[102:103], v[108:109]
	v_pk_mul_f32 v[104:105], v[104:105], v[106:107]
	v_max_f32_e32 v107, 0, v101
	v_max_f32_e32 v109, 0, v99
	v_max_f32_e32 v106, 0, v100
	v_max_f32_e32 v108, 0, v98
	v_pk_mul_f32 v[98:99], v[98:99], v[108:109]
	v_pk_mul_f32 v[100:101], v[100:101], v[106:107]
	v_pk_mul_f32 v[104:105], v[104:105], v[116:117] op_sel_hi:[1,0]
	v_pk_mul_f32 v[106:107], v[100:101], v[116:117] op_sel_hi:[1,0]
	v_pk_mul_f32 v[100:101], v[98:99], v[116:117] op_sel_hi:[1,0]
	v_pk_mul_f32 v[102:103], v[102:103], v[116:117] op_sel_hi:[1,0]
	s_nop 0
	v_cvt_pk_bf16_f32 v98, v102, v103
	v_cvt_pk_bf16_f32 v99, v104, v105
	v_cvt_pk_bf16_f32 v100, v100, v101
	v_cvt_pk_bf16_f32 v101, v106, v107
	global_store_dwordx4 v[114:115], v[98:101], off offset:256
	ds_read_b128 v[98:101], v147 offset:512
	v_or_b32_e32 v102, 32, v148
	v_mul_lo_u32 v106, s69, v102
	v_mad_u64_u32 v[102:103], s[16:17], s68, v102, 0
	s_waitcnt lgkmcnt(0)
	v_mov_b32_e32 v104, v99
	v_mov_b32_e32 v105, v100
	v_mov_b32_e32 v99, v101
	v_pk_add_f32 v[98:99], v[104:105], v[98:99]
	v_add3_u32 v103, v103, v149, v106
	v_add_f32_e32 v98, v98, v99
	v_fmamk_f32 v98, v98, 0x3a800000, v155
	v_rsq_f32_e32 v100, v98
	v_lshl_add_u64 v[98:99], v[102:103], 1, s[78:79]
	v_max_f32_e32 v103, 0, v97
	v_max_f32_e32 v102, 0, v96
	v_max_f32_e32 v105, 0, v95
	v_max_f32_e32 v104, 0, v94
	v_mul_f32_e32 v100, v100, v100
	v_pk_mul_f32 v[94:95], v[94:95], v[104:105]
	v_pk_mul_f32 v[96:97], v[96:97], v[102:103]
	v_pk_mul_f32 v[94:95], v[94:95], v[100:101] op_sel_hi:[1,0]
	v_pk_mul_f32 v[96:97], v[96:97], v[100:101] op_sel_hi:[1,0]
	v_max_f32_e32 v103, 0, v93
	v_max_f32_e32 v102, 0, v92
	v_max_f32_e32 v105, 0, v91
	v_max_f32_e32 v104, 0, v90
	v_pk_mul_f32 v[90:91], v[90:91], v[104:105]
	v_pk_mul_f32 v[92:93], v[92:93], v[102:103]
	v_lshl_add_u64 v[98:99], v[98:99], 0, v[140:141]
	v_pk_mul_f32 v[102:103], v[92:93], v[100:101] op_sel_hi:[1,0]
	v_pk_mul_f32 v[92:93], v[90:91], v[100:101] op_sel_hi:[1,0]
	v_cvt_pk_bf16_f32 v90, v94, v95
	v_cvt_pk_bf16_f32 v91, v96, v97
	s_nop 0
	v_cvt_pk_bf16_f32 v92, v92, v93
	v_cvt_pk_bf16_f32 v93, v102, v103
	global_store_dwordx4 v[98:99], v[90:93], off
	s_nop 1
	v_max_f32_e32 v91, 0, v89
	v_max_f32_e32 v93, 0, v87
	v_max_f32_e32 v90, 0, v88
	v_max_f32_e32 v92, 0, v86
	v_pk_mul_f32 v[86:87], v[86:87], v[92:93]
	v_pk_mul_f32 v[88:89], v[88:89], v[90:91]
	v_max_f32_e32 v91, 0, v85
	v_max_f32_e32 v93, 0, v83
	v_max_f32_e32 v90, 0, v84
	v_max_f32_e32 v92, 0, v82
	v_pk_mul_f32 v[82:83], v[82:83], v[92:93]
	v_pk_mul_f32 v[84:85], v[84:85], v[90:91]
	v_pk_mul_f32 v[88:89], v[88:89], v[100:101] op_sel_hi:[1,0]
	v_pk_mul_f32 v[90:91], v[84:85], v[100:101] op_sel_hi:[1,0]
	v_pk_mul_f32 v[84:85], v[82:83], v[100:101] op_sel_hi:[1,0]
	v_pk_mul_f32 v[86:87], v[86:87], v[100:101] op_sel_hi:[1,0]
	s_nop 0
	v_cvt_pk_bf16_f32 v82, v86, v87
	v_cvt_pk_bf16_f32 v83, v88, v89
	v_cvt_pk_bf16_f32 v84, v84, v85
	v_cvt_pk_bf16_f32 v85, v90, v91
	global_store_dwordx4 v[98:99], v[82:85], off offset:256
	ds_read_b128 v[82:85], v147 offset:768
	v_or_b32_e32 v86, 48, v148
	v_mul_lo_u32 v90, s69, v86
	v_mad_u64_u32 v[86:87], s[16:17], s68, v86, 0
	s_waitcnt lgkmcnt(0)
	v_mov_b32_e32 v88, v83
	v_mov_b32_e32 v89, v84
	v_mov_b32_e32 v83, v85
	v_pk_add_f32 v[82:83], v[88:89], v[82:83]
	v_add3_u32 v87, v87, v149, v90
	v_add_f32_e32 v82, v82, v83
	v_fmamk_f32 v82, v82, 0x3a800000, v155
	v_rsq_f32_e32 v84, v82
	v_lshl_add_u64 v[82:83], v[86:87], 1, s[78:79]
	v_max_f32_e32 v87, 0, v81
	v_max_f32_e32 v86, 0, v80
	v_max_f32_e32 v89, 0, v79
	v_max_f32_e32 v88, 0, v78
	v_mul_f32_e32 v84, v84, v84
	v_pk_mul_f32 v[78:79], v[78:79], v[88:89]
	v_pk_mul_f32 v[80:81], v[80:81], v[86:87]
	v_pk_mul_f32 v[78:79], v[78:79], v[84:85] op_sel_hi:[1,0]
	v_pk_mul_f32 v[80:81], v[80:81], v[84:85] op_sel_hi:[1,0]
	v_max_f32_e32 v87, 0, v77
	v_max_f32_e32 v86, 0, v76
	v_max_f32_e32 v89, 0, v75
	v_max_f32_e32 v88, 0, v74
	v_pk_mul_f32 v[74:75], v[74:75], v[88:89]
	v_pk_mul_f32 v[76:77], v[76:77], v[86:87]
	v_lshl_add_u64 v[82:83], v[82:83], 0, v[140:141]
	v_pk_mul_f32 v[86:87], v[76:77], v[84:85] op_sel_hi:[1,0]
	v_pk_mul_f32 v[76:77], v[74:75], v[84:85] op_sel_hi:[1,0]
	v_cvt_pk_bf16_f32 v74, v78, v79
	v_cvt_pk_bf16_f32 v75, v80, v81
	s_nop 0
	v_cvt_pk_bf16_f32 v76, v76, v77
	v_cvt_pk_bf16_f32 v77, v86, v87
	global_store_dwordx4 v[82:83], v[74:77], off
	s_nop 1
	v_max_f32_e32 v75, 0, v73
	v_max_f32_e32 v77, 0, v71
	v_max_f32_e32 v74, 0, v72
	v_max_f32_e32 v76, 0, v70
	v_pk_mul_f32 v[70:71], v[70:71], v[76:77]
	v_pk_mul_f32 v[72:73], v[72:73], v[74:75]
	v_max_f32_e32 v75, 0, v69
	v_max_f32_e32 v77, 0, v67
	v_max_f32_e32 v74, 0, v68
	v_max_f32_e32 v76, 0, v66
	v_pk_mul_f32 v[66:67], v[66:67], v[76:77]
	v_pk_mul_f32 v[68:69], v[68:69], v[74:75]
	v_pk_mul_f32 v[72:73], v[72:73], v[84:85] op_sel_hi:[1,0]
	v_pk_mul_f32 v[74:75], v[68:69], v[84:85] op_sel_hi:[1,0]
	v_pk_mul_f32 v[68:69], v[66:67], v[84:85] op_sel_hi:[1,0]
	v_pk_mul_f32 v[70:71], v[70:71], v[84:85] op_sel_hi:[1,0]
	s_nop 0
	v_cvt_pk_bf16_f32 v66, v70, v71
	v_cvt_pk_bf16_f32 v67, v72, v73
	v_cvt_pk_bf16_f32 v68, v68, v69
	v_cvt_pk_bf16_f32 v69, v74, v75
	global_store_dwordx4 v[82:83], v[66:69], off offset:256
	ds_read_b128 v[66:69], v147 offset:1024
	v_add_u32_e32 v70, 0x80, v148
	v_ashrrev_i32_e32 v71, 31, v70
	v_mul_lo_u32 v74, s68, v71
	v_mul_lo_u32 v75, s69, v70
	s_waitcnt lgkmcnt(0)
	v_mov_b32_e32 v72, v67
	v_mov_b32_e32 v73, v68
	v_mov_b32_e32 v67, v69
	v_pk_add_f32 v[66:67], v[72:73], v[66:67]
	v_mad_u64_u32 v[70:71], s[16:17], s68, v70, 0
	v_add_f32_e32 v66, v66, v67
	v_fmamk_f32 v66, v66, 0x3a800000, v155
	v_add3_u32 v71, v71, v74, v75
	v_rsq_f32_e32 v68, v66
	v_lshl_add_u64 v[66:67], v[70:71], 1, s[78:79]
	v_max_f32_e32 v71, 0, v65
	v_max_f32_e32 v70, 0, v64
	v_max_f32_e32 v73, 0, v63
	v_max_f32_e32 v72, 0, v62
	v_mul_f32_e32 v68, v68, v68
	v_pk_mul_f32 v[62:63], v[62:63], v[72:73]
	v_pk_mul_f32 v[64:65], v[64:65], v[70:71]
	v_pk_mul_f32 v[62:63], v[62:63], v[68:69] op_sel_hi:[1,0]
	v_pk_mul_f32 v[64:65], v[64:65], v[68:69] op_sel_hi:[1,0]
	v_max_f32_e32 v71, 0, v61
	v_max_f32_e32 v70, 0, v60
	v_max_f32_e32 v73, 0, v59
	v_max_f32_e32 v72, 0, v58
	v_pk_mul_f32 v[58:59], v[58:59], v[72:73]
	v_pk_mul_f32 v[60:61], v[60:61], v[70:71]
	v_lshl_add_u64 v[66:67], v[66:67], 0, v[140:141]
	v_pk_mul_f32 v[70:71], v[60:61], v[68:69] op_sel_hi:[1,0]
	v_pk_mul_f32 v[60:61], v[58:59], v[68:69] op_sel_hi:[1,0]
	v_cvt_pk_bf16_f32 v58, v62, v63
	v_cvt_pk_bf16_f32 v59, v64, v65
	s_nop 0
	v_cvt_pk_bf16_f32 v60, v60, v61
	v_cvt_pk_bf16_f32 v61, v70, v71
	global_store_dwordx4 v[66:67], v[58:61], off
	s_nop 1
	v_max_f32_e32 v59, 0, v57
	v_max_f32_e32 v61, 0, v55
	v_max_f32_e32 v58, 0, v56
	v_max_f32_e32 v60, 0, v54
	v_pk_mul_f32 v[54:55], v[54:55], v[60:61]
	v_pk_mul_f32 v[56:57], v[56:57], v[58:59]
	v_max_f32_e32 v59, 0, v53
	v_max_f32_e32 v61, 0, v51
	v_max_f32_e32 v58, 0, v52
	v_max_f32_e32 v60, 0, v50
	v_pk_mul_f32 v[50:51], v[50:51], v[60:61]
	v_pk_mul_f32 v[52:53], v[52:53], v[58:59]
	v_pk_mul_f32 v[56:57], v[56:57], v[68:69] op_sel_hi:[1,0]
	v_pk_mul_f32 v[58:59], v[52:53], v[68:69] op_sel_hi:[1,0]
	v_pk_mul_f32 v[52:53], v[50:51], v[68:69] op_sel_hi:[1,0]
	v_pk_mul_f32 v[54:55], v[54:55], v[68:69] op_sel_hi:[1,0]
	s_nop 0
	v_cvt_pk_bf16_f32 v50, v54, v55
	v_cvt_pk_bf16_f32 v51, v56, v57
	v_cvt_pk_bf16_f32 v52, v52, v53
	v_cvt_pk_bf16_f32 v53, v58, v59
	global_store_dwordx4 v[66:67], v[50:53], off offset:256
	ds_read_b128 v[50:53], v147 offset:1280
	v_add_u32_e32 v54, 0x90, v148
	v_ashrrev_i32_e32 v55, 31, v54
	v_mul_lo_u32 v58, s68, v55
	v_mul_lo_u32 v59, s69, v54
	s_waitcnt lgkmcnt(0)
	v_mov_b32_e32 v56, v51
	v_mov_b32_e32 v57, v52
	v_mov_b32_e32 v51, v53
	v_pk_add_f32 v[50:51], v[56:57], v[50:51]
	v_mad_u64_u32 v[54:55], s[16:17], s68, v54, 0
	v_add_f32_e32 v50, v50, v51
	v_fmamk_f32 v50, v50, 0x3a800000, v155
	v_add3_u32 v55, v55, v58, v59
	v_rsq_f32_e32 v52, v50
	v_lshl_add_u64 v[50:51], v[54:55], 1, s[78:79]
	v_max_f32_e32 v55, 0, v49
	v_max_f32_e32 v54, 0, v48
	v_max_f32_e32 v57, 0, v47
	v_max_f32_e32 v56, 0, v46
	v_mul_f32_e32 v52, v52, v52
	v_pk_mul_f32 v[46:47], v[46:47], v[56:57]
	v_pk_mul_f32 v[48:49], v[48:49], v[54:55]
	v_pk_mul_f32 v[46:47], v[46:47], v[52:53] op_sel_hi:[1,0]
	v_pk_mul_f32 v[48:49], v[48:49], v[52:53] op_sel_hi:[1,0]
	v_max_f32_e32 v55, 0, v45
	v_max_f32_e32 v54, 0, v44
	v_max_f32_e32 v57, 0, v43
	v_max_f32_e32 v56, 0, v42
	v_pk_mul_f32 v[42:43], v[42:43], v[56:57]
	v_pk_mul_f32 v[44:45], v[44:45], v[54:55]
	v_lshl_add_u64 v[50:51], v[50:51], 0, v[140:141]
	v_pk_mul_f32 v[54:55], v[44:45], v[52:53] op_sel_hi:[1,0]
	v_pk_mul_f32 v[44:45], v[42:43], v[52:53] op_sel_hi:[1,0]
	v_cvt_pk_bf16_f32 v42, v46, v47
	v_cvt_pk_bf16_f32 v43, v48, v49
	s_nop 0
	v_cvt_pk_bf16_f32 v44, v44, v45
	v_cvt_pk_bf16_f32 v45, v54, v55
	global_store_dwordx4 v[50:51], v[42:45], off
	s_nop 1
	v_max_f32_e32 v43, 0, v41
	v_max_f32_e32 v45, 0, v39
	v_max_f32_e32 v42, 0, v40
	v_max_f32_e32 v44, 0, v38
	v_pk_mul_f32 v[38:39], v[38:39], v[44:45]
	v_pk_mul_f32 v[40:41], v[40:41], v[42:43]
	v_max_f32_e32 v43, 0, v37
	v_max_f32_e32 v45, 0, v35
	v_max_f32_e32 v42, 0, v36
	v_max_f32_e32 v44, 0, v34
	v_pk_mul_f32 v[34:35], v[34:35], v[44:45]
	v_pk_mul_f32 v[36:37], v[36:37], v[42:43]
	v_pk_mul_f32 v[40:41], v[40:41], v[52:53] op_sel_hi:[1,0]
	v_pk_mul_f32 v[42:43], v[36:37], v[52:53] op_sel_hi:[1,0]
	v_pk_mul_f32 v[36:37], v[34:35], v[52:53] op_sel_hi:[1,0]
	v_pk_mul_f32 v[38:39], v[38:39], v[52:53] op_sel_hi:[1,0]
	s_nop 0
	v_cvt_pk_bf16_f32 v34, v38, v39
	v_cvt_pk_bf16_f32 v35, v40, v41
	v_cvt_pk_bf16_f32 v36, v36, v37
	v_cvt_pk_bf16_f32 v37, v42, v43
	global_store_dwordx4 v[50:51], v[34:37], off offset:256
	ds_read_b128 v[34:37], v147 offset:1536
	v_add_u32_e32 v38, 0xa0, v148
	v_ashrrev_i32_e32 v39, 31, v38
	v_mul_lo_u32 v42, s68, v39
	v_mul_lo_u32 v43, s69, v38
	s_waitcnt lgkmcnt(0)
	v_mov_b32_e32 v40, v35
	v_mov_b32_e32 v41, v36
	v_mov_b32_e32 v35, v37
	v_pk_add_f32 v[34:35], v[40:41], v[34:35]
	v_mad_u64_u32 v[38:39], s[16:17], s68, v38, 0
	v_add_f32_e32 v34, v34, v35
	v_fmamk_f32 v34, v34, 0x3a800000, v155
	v_add3_u32 v39, v39, v42, v43
	v_rsq_f32_e32 v36, v34
	v_lshl_add_u64 v[34:35], v[38:39], 1, s[78:79]
	v_max_f32_e32 v39, 0, v33
	v_max_f32_e32 v38, 0, v32
	v_max_f32_e32 v41, 0, v31
	v_max_f32_e32 v40, 0, v30
	v_mul_f32_e32 v36, v36, v36
	v_pk_mul_f32 v[30:31], v[30:31], v[40:41]
	v_pk_mul_f32 v[32:33], v[32:33], v[38:39]
	v_pk_mul_f32 v[30:31], v[30:31], v[36:37] op_sel_hi:[1,0]
	v_pk_mul_f32 v[32:33], v[32:33], v[36:37] op_sel_hi:[1,0]
	v_max_f32_e32 v39, 0, v29
	v_max_f32_e32 v38, 0, v28
	v_max_f32_e32 v41, 0, v27
	v_max_f32_e32 v40, 0, v26
	v_pk_mul_f32 v[26:27], v[26:27], v[40:41]
	v_pk_mul_f32 v[28:29], v[28:29], v[38:39]
	v_lshl_add_u64 v[34:35], v[34:35], 0, v[140:141]
	v_pk_mul_f32 v[38:39], v[28:29], v[36:37] op_sel_hi:[1,0]
	v_pk_mul_f32 v[28:29], v[26:27], v[36:37] op_sel_hi:[1,0]
	v_cvt_pk_bf16_f32 v26, v30, v31
	v_cvt_pk_bf16_f32 v27, v32, v33
	s_nop 0
	v_cvt_pk_bf16_f32 v28, v28, v29
	v_cvt_pk_bf16_f32 v29, v38, v39
	global_store_dwordx4 v[34:35], v[26:29], off
	s_nop 1
	v_max_f32_e32 v27, 0, v25
	v_max_f32_e32 v29, 0, v23
	v_max_f32_e32 v26, 0, v24
	v_max_f32_e32 v28, 0, v22
	v_pk_mul_f32 v[22:23], v[22:23], v[28:29]
	v_pk_mul_f32 v[24:25], v[24:25], v[26:27]
	v_max_f32_e32 v27, 0, v21
	v_max_f32_e32 v29, 0, v19
	v_max_f32_e32 v26, 0, v20
	v_max_f32_e32 v28, 0, v18
	v_pk_mul_f32 v[18:19], v[18:19], v[28:29]
	v_pk_mul_f32 v[20:21], v[20:21], v[26:27]
	v_pk_mul_f32 v[24:25], v[24:25], v[36:37] op_sel_hi:[1,0]
	v_pk_mul_f32 v[26:27], v[20:21], v[36:37] op_sel_hi:[1,0]
	v_pk_mul_f32 v[20:21], v[18:19], v[36:37] op_sel_hi:[1,0]
	v_pk_mul_f32 v[22:23], v[22:23], v[36:37] op_sel_hi:[1,0]
	s_nop 0
	v_cvt_pk_bf16_f32 v18, v22, v23
	v_cvt_pk_bf16_f32 v19, v24, v25
	v_cvt_pk_bf16_f32 v20, v20, v21
	v_cvt_pk_bf16_f32 v21, v26, v27
	global_store_dwordx4 v[34:35], v[18:21], off offset:256
	ds_read_b128 v[18:21], v147 offset:1792
	v_add_u32_e32 v22, 0xb0, v148
	v_ashrrev_i32_e32 v23, 31, v22
	v_mul_lo_u32 v26, s68, v23
	v_mul_lo_u32 v27, s69, v22
	s_waitcnt lgkmcnt(0)
	v_mov_b32_e32 v24, v19
	v_mov_b32_e32 v25, v20
	v_mov_b32_e32 v19, v21
	v_pk_add_f32 v[18:19], v[24:25], v[18:19]
	v_mad_u64_u32 v[22:23], s[16:17], s68, v22, 0
	v_add_f32_e32 v18, v18, v19
	v_fmamk_f32 v18, v18, 0x3a800000, v155
	v_add3_u32 v23, v23, v26, v27
	v_rsq_f32_e32 v20, v18
	v_lshl_add_u64 v[18:19], v[22:23], 1, s[78:79]
	v_max_f32_e32 v23, 0, v17
	v_max_f32_e32 v22, 0, v16
	v_max_f32_e32 v25, 0, v15
	v_max_f32_e32 v24, 0, v14
	v_mul_f32_e32 v20, v20, v20
	v_pk_mul_f32 v[14:15], v[14:15], v[24:25]
	v_pk_mul_f32 v[16:17], v[16:17], v[22:23]
	v_pk_mul_f32 v[14:15], v[14:15], v[20:21] op_sel_hi:[1,0]
	v_pk_mul_f32 v[16:17], v[16:17], v[20:21] op_sel_hi:[1,0]
	v_max_f32_e32 v23, 0, v13
	v_max_f32_e32 v22, 0, v12
	v_max_f32_e32 v25, 0, v11
	v_max_f32_e32 v24, 0, v10
	v_pk_mul_f32 v[10:11], v[10:11], v[24:25]
	v_pk_mul_f32 v[12:13], v[12:13], v[22:23]
	v_lshl_add_u64 v[18:19], v[18:19], 0, v[140:141]
	v_pk_mul_f32 v[22:23], v[12:13], v[20:21] op_sel_hi:[1,0]
	v_pk_mul_f32 v[12:13], v[10:11], v[20:21] op_sel_hi:[1,0]
	v_cvt_pk_bf16_f32 v10, v14, v15
	v_cvt_pk_bf16_f32 v11, v16, v17
	s_nop 0
	v_cvt_pk_bf16_f32 v12, v12, v13
	v_cvt_pk_bf16_f32 v13, v22, v23
	global_store_dwordx4 v[18:19], v[10:13], off
	s_nop 1
	v_max_f32_e32 v11, 0, v9
	v_max_f32_e32 v13, 0, v7
	v_max_f32_e32 v10, 0, v8
	v_max_f32_e32 v12, 0, v6
	v_pk_mul_f32 v[6:7], v[6:7], v[12:13]
	v_pk_mul_f32 v[8:9], v[8:9], v[10:11]
	v_max_f32_e32 v11, 0, v5
	v_max_f32_e32 v13, 0, v3
	v_max_f32_e32 v10, 0, v4
	v_max_f32_e32 v12, 0, v2
	v_pk_mul_f32 v[2:3], v[2:3], v[12:13]
	v_pk_mul_f32 v[4:5], v[4:5], v[10:11]
	v_pk_mul_f32 v[8:9], v[8:9], v[20:21] op_sel_hi:[1,0]
	v_pk_mul_f32 v[10:11], v[4:5], v[20:21] op_sel_hi:[1,0]
	v_pk_mul_f32 v[4:5], v[2:3], v[20:21] op_sel_hi:[1,0]
	v_pk_mul_f32 v[6:7], v[6:7], v[20:21] op_sel_hi:[1,0]
	s_nop 0
	v_cvt_pk_bf16_f32 v2, v6, v7
	v_cvt_pk_bf16_f32 v3, v8, v9
	v_cvt_pk_bf16_f32 v4, v4, v5
	v_cvt_pk_bf16_f32 v5, v10, v11
	global_store_dwordx4 v[18:19], v[2:5], off offset:256
	s_cbranch_vccnz .LBB0_325
	s_nop 0
	v_lshl_add_u32 v2, s61, 8, v145
	v_ashrrev_i32_e32 v3, 31, v2
	s_mov_b32 m0, s18
	v_lshl_add_u64 v[2:3], v[2:3], 4, s[96:97]
	s_mov_b64 s[6:7], 0x800
	global_load_lds_dwordx4 v[2:3], off
	v_lshl_add_u64 v[2:3], v[2:3], 0, s[6:7]
	s_add_i32 m0, s18, 0x400
	s_andn2_b64 vcc, exec, s[8:9]
	global_load_lds_dwordx4 v[2:3], off
	s_cbranch_vccnz .LBB0_324
	s_mov_b32 s100, 1
	s_branch .LBB0_324

.LBB0_359:
	s_add_u32 s2, s2, 0x80
	s_addc_u32 s3, s3, 0
	s_add_u32 s19, s10, 0x100
	v_mov_b32_e32 v2, 0
	s_addc_u32 s29, s11, 0
	s_mov_b32 s10, 0
	v_mov_b32_e32 v3, v2
	s_waitcnt lgkmcnt(0)
	v_mov_b32_e32 v4, v2
	v_mov_b32_e32 v5, v2
	v_mov_b32_e32 v6, v2
	v_mov_b32_e32 v7, v2
	v_mov_b32_e32 v8, v2
	v_mov_b32_e32 v9, v2
	v_mov_b32_e32 v18, v2
	v_mov_b32_e32 v19, v2
	v_mov_b32_e32 v20, v2
	v_mov_b32_e32 v21, v2
	v_mov_b32_e32 v22, v2
	v_mov_b32_e32 v23, v2
	v_mov_b32_e32 v24, v2
	v_mov_b32_e32 v25, v2
	v_mov_b32_e32 v34, v2
	v_mov_b32_e32 v35, v2
	v_mov_b32_e32 v36, v2
	v_mov_b32_e32 v37, v2
	v_mov_b32_e32 v38, v2
	v_mov_b32_e32 v39, v2
	v_mov_b32_e32 v40, v2
	v_mov_b32_e32 v41, v2
	v_mov_b32_e32 v50, v2
	v_mov_b32_e32 v51, v2
	v_mov_b32_e32 v52, v2
	v_mov_b32_e32 v53, v2
	v_mov_b32_e32 v54, v2
	v_mov_b32_e32 v55, v2
	v_mov_b32_e32 v56, v2
	v_mov_b32_e32 v57, v2
	v_mov_b32_e32 v10, v2
	v_mov_b32_e32 v11, v2
	v_mov_b32_e32 v12, v2
	v_mov_b32_e32 v13, v2
	v_mov_b32_e32 v14, v2
	v_mov_b32_e32 v15, v2
	v_mov_b32_e32 v16, v2
	v_mov_b32_e32 v17, v2
	v_mov_b32_e32 v26, v2
	v_mov_b32_e32 v27, v2
	v_mov_b32_e32 v28, v2
	v_mov_b32_e32 v29, v2
	v_mov_b32_e32 v30, v2
	v_mov_b32_e32 v31, v2
	v_mov_b32_e32 v32, v2
	v_mov_b32_e32 v33, v2
	v_mov_b32_e32 v42, v2
	v_mov_b32_e32 v43, v2
	v_mov_b32_e32 v44, v2
	v_mov_b32_e32 v45, v2
	v_mov_b32_e32 v46, v2
	v_mov_b32_e32 v47, v2
	v_mov_b32_e32 v48, v2
	v_mov_b32_e32 v49, v2
	v_mov_b32_e32 v58, v2
	v_mov_b32_e32 v59, v2
	v_mov_b32_e32 v60, v2
	v_mov_b32_e32 v61, v2
	v_mov_b32_e32 v62, v2
	v_mov_b32_e32 v63, v2
	v_mov_b32_e32 v64, v2
	v_mov_b32_e32 v65, v2
	v_mov_b32_e32 v66, v2
	v_mov_b32_e32 v67, v2
	v_mov_b32_e32 v68, v2
	v_mov_b32_e32 v69, v2
	v_mov_b32_e32 v70, v2
	v_mov_b32_e32 v71, v2
	v_mov_b32_e32 v72, v2
	v_mov_b32_e32 v73, v2
	v_mov_b32_e32 v82, v2
	v_mov_b32_e32 v83, v2
	v_mov_b32_e32 v84, v2
	v_mov_b32_e32 v85, v2
	v_mov_b32_e32 v86, v2
	v_mov_b32_e32 v87, v2
	v_mov_b32_e32 v88, v2
	v_mov_b32_e32 v89, v2
	v_mov_b32_e32 v98, v2
	v_mov_b32_e32 v99, v2
	v_mov_b32_e32 v100, v2
	v_mov_b32_e32 v101, v2
	v_mov_b32_e32 v102, v2
	v_mov_b32_e32 v103, v2
	v_mov_b32_e32 v104, v2
	v_mov_b32_e32 v105, v2
	v_mov_b32_e32 v114, v2
	v_mov_b32_e32 v115, v2
	v_mov_b32_e32 v116, v2
	v_mov_b32_e32 v117, v2
	v_mov_b32_e32 v118, v2
	v_mov_b32_e32 v119, v2
	v_mov_b32_e32 v120, v2
	v_mov_b32_e32 v121, v2
	v_mov_b32_e32 v74, v2
	v_mov_b32_e32 v75, v2
	v_mov_b32_e32 v76, v2
	v_mov_b32_e32 v77, v2
	v_mov_b32_e32 v78, v2
	v_mov_b32_e32 v79, v2
	v_mov_b32_e32 v80, v2
	v_mov_b32_e32 v81, v2
	v_mov_b32_e32 v90, v2
	v_mov_b32_e32 v91, v2
	v_mov_b32_e32 v92, v2
	v_mov_b32_e32 v93, v2
	v_mov_b32_e32 v94, v2
	v_mov_b32_e32 v95, v2
	v_mov_b32_e32 v96, v2
	v_mov_b32_e32 v97, v2
	v_mov_b32_e32 v106, v2
	v_mov_b32_e32 v107, v2
	v_mov_b32_e32 v108, v2
	v_mov_b32_e32 v109, v2
	v_mov_b32_e32 v110, v2
	v_mov_b32_e32 v111, v2
	v_mov_b32_e32 v112, v2
	v_mov_b32_e32 v113, v2
	v_mov_b32_e32 v122, v2
	v_mov_b32_e32 v123, v2
	v_mov_b32_e32 v124, v2
	v_mov_b32_e32 v125, v2
	v_mov_b32_e32 v126, v2
	v_mov_b32_e32 v127, v2
	v_mov_b32_e32 v128, v2
	v_mov_b32_e32 v129, v2
	s_cmp_eq_u32 s100, 1
	s_cbranch_scc0 .Ldb_360
	s_mov_b32 s100, 0
	s_barrier
.Ldb_360:
.LBB0_360:
	s_add_i32 s30, s10, 2
	s_add_u32 s31, s2, 0x80
	s_addc_u32 s11, s3, 0
	s_add_i32 s35, 0, 0x10000
	s_cmp_eq_u32 s58, s10
	s_cselect_b32 s11, s1, s11
	s_cselect_b32 s10, s0, s31
	v_add_u32_e32 v148, s35, v160
	s_cselect_b32 s67, s7, s29
	s_cselect_b32 s66, s6, s19
	s_add_i32 s31, 0, 0x14000
	ds_read_b128 v[140:143], v148
	ds_read_b128 v[144:147], v148 offset:1024
	ds_read_b128 v[180:183], v148 offset:2048
	ds_read_b128 v[184:187], v148 offset:3072
	v_add_u32_e32 v148, s31, v160
	ds_read_b128 v[188:191], v148
	ds_read_b128 v[192:195], v148 offset:1024
	ds_read_b128 v[196:199], v148 offset:2048
	ds_read_b128 v[200:203], v148 offset:3072
	v_lshl_add_u64 v[148:149], s[2:3], 0, v[136:137]
	s_add_i32 m0, s23, 0xc000
	ds_read_b128 v[204:207], v172
	ds_read_b128 v[208:211], v172 offset:1024
	ds_read_b128 v[212:215], v172 offset:2048
	ds_read_b128 v[216:219], v172 offset:3072
	ds_read_b128 v[220:223], v172 offset:4096
	ds_read_b128 v[224:227], v172 offset:5120
	ds_read_b128 v[228:231], v172 offset:6144
	ds_read_b128 v[232:235], v172 offset:7168
	global_load_lds_dwordx4 v[148:149], off
	v_lshl_add_u64 v[148:149], s[2:3], 0, v[138:139]
	s_add_i32 m0, s23, 0xe000
	s_nop 0
	global_load_lds_dwordx4 v[148:149], off
	s_waitcnt vmcnt(8)
	s_waitcnt lgkmcnt(0)
	s_barrier
	s_waitcnt lgkmcnt(0)
	v_mfma_f32_16x16x32_bf16 v[126:129], v[140:143], v[204:207], v[126:129]
	v_mfma_f32_16x16x32_bf16 v[122:125], v[180:183], v[204:207], v[122:125]
	v_mfma_f32_16x16x32_bf16 v[110:113], v[140:143], v[212:215], v[110:113]
	v_mfma_f32_16x16x32_bf16 v[106:109], v[180:183], v[212:215], v[106:109]
	v_mfma_f32_16x16x32_bf16 v[94:97], v[140:143], v[220:223], v[94:97]
	v_mfma_f32_16x16x32_bf16 v[90:93], v[180:183], v[220:223], v[90:93]
	v_mfma_f32_16x16x32_bf16 v[78:81], v[140:143], v[228:231], v[78:81]
	v_mfma_f32_16x16x32_bf16 v[74:77], v[180:183], v[228:231], v[74:77]
	v_mfma_f32_16x16x32_bf16 v[126:129], v[144:147], v[208:211], v[126:129]
	v_mfma_f32_16x16x32_bf16 v[122:125], v[184:187], v[208:211], v[122:125]
	v_mfma_f32_16x16x32_bf16 v[110:113], v[144:147], v[216:219], v[110:113]
	v_mfma_f32_16x16x32_bf16 v[106:109], v[184:187], v[216:219], v[106:109]
	v_mfma_f32_16x16x32_bf16 v[94:97], v[144:147], v[224:227], v[94:97]
	v_mfma_f32_16x16x32_bf16 v[90:93], v[184:187], v[224:227], v[90:93]
	v_mfma_f32_16x16x32_bf16 v[78:81], v[144:147], v[232:235], v[78:81]
	v_mfma_f32_16x16x32_bf16 v[74:77], v[184:187], v[232:235], v[74:77]
	v_mfma_f32_16x16x32_bf16 v[118:121], v[188:191], v[204:207], v[118:121]
	v_mfma_f32_16x16x32_bf16 v[114:117], v[196:199], v[204:207], v[114:117]
	v_mfma_f32_16x16x32_bf16 v[102:105], v[188:191], v[212:215], v[102:105]
	v_mfma_f32_16x16x32_bf16 v[98:101], v[196:199], v[212:215], v[98:101]
	v_mfma_f32_16x16x32_bf16 v[86:89], v[188:191], v[220:223], v[86:89]
	v_mfma_f32_16x16x32_bf16 v[82:85], v[196:199], v[220:223], v[82:85]
	v_mfma_f32_16x16x32_bf16 v[70:73], v[188:191], v[228:231], v[70:73]
	v_mfma_f32_16x16x32_bf16 v[66:69], v[196:199], v[228:231], v[66:69]
	v_mfma_f32_16x16x32_bf16 v[118:121], v[192:195], v[208:211], v[118:121]
	v_mfma_f32_16x16x32_bf16 v[114:117], v[200:203], v[208:211], v[114:117]
	v_mfma_f32_16x16x32_bf16 v[102:105], v[192:195], v[216:219], v[102:105]
	v_mfma_f32_16x16x32_bf16 v[98:101], v[200:203], v[216:219], v[98:101]
	v_mfma_f32_16x16x32_bf16 v[86:89], v[192:195], v[224:227], v[86:89]
	v_mfma_f32_16x16x32_bf16 v[82:85], v[200:203], v[224:227], v[82:85]
	v_mfma_f32_16x16x32_bf16 v[70:73], v[192:195], v[232:235], v[70:73]
	v_mfma_f32_16x16x32_bf16 v[66:69], v[200:203], v[232:235], v[66:69]
	s_barrier
	s_add_i32 s35, s35, s20
	v_lshl_add_u64 v[148:149], s[66:67], 0, v[0:1]
	s_mov_b32 m0, s35
	ds_read_b128 v[204:207], v172 offset:16384
	ds_read_b128 v[208:211], v172 offset:17408
	ds_read_b128 v[212:215], v172 offset:18432
	ds_read_b128 v[216:219], v172 offset:19456
	ds_read_b128 v[220:223], v172 offset:20480
	ds_read_b128 v[224:227], v172 offset:21504
	ds_read_b128 v[228:231], v172 offset:22528
	ds_read_b128 v[232:235], v172 offset:23552
	global_load_lds_dwordx4 v[148:149], off
	s_add_i32 m0, s35, 0x2000
	v_lshl_add_u64 v[236:237], s[66:67], 0, v[134:135]
	s_add_u32 s66, s66, s16
	s_addc_u32 s67, s67, 0
	s_add_i32 s31, s31, s20
	global_load_lds_dwordx4 v[236:237], off
	v_lshl_add_u64 v[238:239], s[66:67], 0, v[0:1]
	s_mov_b32 m0, s31
	v_lshl_add_u64 v[240:241], s[66:67], 0, v[134:135]
	global_load_lds_dwordx4 v[238:239], off
	s_add_i32 m0, s31, 0x2000
	v_lshl_add_u64 v[242:243], s[10:11], 0, v[130:131]
	global_load_lds_dwordx4 v[240:241], off
	s_mov_b32 m0, s23
	v_lshl_add_u64 v[244:245], s[10:11], 0, v[132:133]
	global_load_lds_dwordx4 v[242:243], off
	s_mov_b32 m0, s52
	s_nop 0
	global_load_lds_dwordx4 v[244:245], off
	s_waitcnt vmcnt(8)
	s_waitcnt lgkmcnt(0)
	s_barrier
	s_waitcnt lgkmcnt(0)
	v_mfma_f32_16x16x32_bf16 v[62:65], v[140:143], v[204:207], v[62:65]
	v_mfma_f32_16x16x32_bf16 v[58:61], v[180:183], v[204:207], v[58:61]
	v_mfma_f32_16x16x32_bf16 v[46:49], v[140:143], v[212:215], v[46:49]
	v_mfma_f32_16x16x32_bf16 v[42:45], v[180:183], v[212:215], v[42:45]
	v_mfma_f32_16x16x32_bf16 v[30:33], v[140:143], v[220:223], v[30:33]
	v_mfma_f32_16x16x32_bf16 v[26:29], v[180:183], v[220:223], v[26:29]
	v_mfma_f32_16x16x32_bf16 v[14:17], v[140:143], v[228:231], v[14:17]
	v_mfma_f32_16x16x32_bf16 v[10:13], v[180:183], v[228:231], v[10:13]
	v_mfma_f32_16x16x32_bf16 v[62:65], v[144:147], v[208:211], v[62:65]
	v_mfma_f32_16x16x32_bf16 v[58:61], v[184:187], v[208:211], v[58:61]
	v_mfma_f32_16x16x32_bf16 v[46:49], v[144:147], v[216:219], v[46:49]
	v_mfma_f32_16x16x32_bf16 v[42:45], v[184:187], v[216:219], v[42:45]
	v_mfma_f32_16x16x32_bf16 v[30:33], v[144:147], v[224:227], v[30:33]
	v_mfma_f32_16x16x32_bf16 v[26:29], v[184:187], v[224:227], v[26:29]
	v_mfma_f32_16x16x32_bf16 v[14:17], v[144:147], v[232:235], v[14:17]
	v_mfma_f32_16x16x32_bf16 v[10:13], v[184:187], v[232:235], v[10:13]
	v_mfma_f32_16x16x32_bf16 v[54:57], v[188:191], v[204:207], v[54:57]
	v_mfma_f32_16x16x32_bf16 v[50:53], v[196:199], v[204:207], v[50:53]
	v_mfma_f32_16x16x32_bf16 v[38:41], v[188:191], v[212:215], v[38:41]
	v_mfma_f32_16x16x32_bf16 v[34:37], v[196:199], v[212:215], v[34:37]
	v_mfma_f32_16x16x32_bf16 v[22:25], v[188:191], v[220:223], v[22:25]
	v_mfma_f32_16x16x32_bf16 v[18:21], v[196:199], v[220:223], v[18:21]
	v_mfma_f32_16x16x32_bf16 v[6:9], v[188:191], v[228:231], v[6:9]
	v_mfma_f32_16x16x32_bf16 v[2:5], v[196:199], v[228:231], v[2:5]
	v_mfma_f32_16x16x32_bf16 v[54:57], v[192:195], v[208:211], v[54:57]
	v_mfma_f32_16x16x32_bf16 v[50:53], v[200:203], v[208:211], v[50:53]
	v_mfma_f32_16x16x32_bf16 v[38:41], v[192:195], v[216:219], v[38:41]
	v_mfma_f32_16x16x32_bf16 v[34:37], v[200:203], v[216:219], v[34:37]
	v_mfma_f32_16x16x32_bf16 v[22:25], v[192:195], v[224:227], v[22:25]
	v_mfma_f32_16x16x32_bf16 v[18:21], v[200:203], v[224:227], v[18:21]
	v_mfma_f32_16x16x32_bf16 v[6:9], v[192:195], v[232:235], v[6:9]
	v_mfma_f32_16x16x32_bf16 v[2:5], v[200:203], v[232:235], v[2:5]
	s_barrier
	s_add_i32 s31, 0, 0x18000
	s_add_i32 s35, 0, 0x1c000
	v_add_u32_e32 v184, s31, v160
	v_add_u32_e32 v200, s35, v160
	ds_read_b128 v[140:143], v184
	ds_read_b128 v[144:147], v184 offset:1024
	ds_read_b128 v[180:183], v184 offset:2048
	ds_read_b128 v[184:187], v184 offset:3072
	ds_read_b128 v[188:191], v200
	ds_read_b128 v[192:195], v200 offset:1024
	ds_read_b128 v[196:199], v200 offset:2048
	ds_read_b128 v[200:203], v200 offset:3072
	s_add_u32 s10, s10, s16
	s_addc_u32 s11, s11, 0
	s_mov_b32 m0, s53
	v_lshl_add_u64 v[246:247], s[10:11], 0, v[130:131]
	ds_read_b128 v[204:207], v172 offset:32768
	ds_read_b128 v[208:211], v172 offset:33792
	ds_read_b128 v[212:215], v172 offset:34816
	ds_read_b128 v[216:219], v172 offset:35840
	ds_read_b128 v[220:223], v172 offset:36864
	ds_read_b128 v[224:227], v172 offset:37888
	ds_read_b128 v[228:231], v172 offset:38912
	ds_read_b128 v[232:235], v172 offset:39936
	global_load_lds_dwordx4 v[246:247], off
	v_lshl_add_u64 v[246:247], s[10:11], 0, v[132:133]
	s_mov_b32 m0, s54
	s_nop 0
	global_load_lds_dwordx4 v[246:247], off
	s_waitcnt vmcnt(8)
	s_waitcnt lgkmcnt(0)
	s_barrier
	s_waitcnt lgkmcnt(0)
	v_mfma_f32_16x16x32_bf16 v[126:129], v[140:143], v[204:207], v[126:129]
	v_mfma_f32_16x16x32_bf16 v[122:125], v[180:183], v[204:207], v[122:125]
	v_mfma_f32_16x16x32_bf16 v[110:113], v[140:143], v[212:215], v[110:113]
	v_mfma_f32_16x16x32_bf16 v[106:109], v[180:183], v[212:215], v[106:109]
	v_mfma_f32_16x16x32_bf16 v[94:97], v[140:143], v[220:223], v[94:97]
	v_mfma_f32_16x16x32_bf16 v[90:93], v[180:183], v[220:223], v[90:93]
	v_mfma_f32_16x16x32_bf16 v[78:81], v[140:143], v[228:231], v[78:81]
	v_mfma_f32_16x16x32_bf16 v[74:77], v[180:183], v[228:231], v[74:77]
	v_mfma_f32_16x16x32_bf16 v[126:129], v[144:147], v[208:211], v[126:129]
	v_mfma_f32_16x16x32_bf16 v[122:125], v[184:187], v[208:211], v[122:125]
	v_mfma_f32_16x16x32_bf16 v[110:113], v[144:147], v[216:219], v[110:113]
	v_mfma_f32_16x16x32_bf16 v[106:109], v[184:187], v[216:219], v[106:109]
	v_mfma_f32_16x16x32_bf16 v[94:97], v[144:147], v[224:227], v[94:97]
	v_mfma_f32_16x16x32_bf16 v[90:93], v[184:187], v[224:227], v[90:93]
	v_mfma_f32_16x16x32_bf16 v[78:81], v[144:147], v[232:235], v[78:81]
	v_mfma_f32_16x16x32_bf16 v[74:77], v[184:187], v[232:235], v[74:77]
	v_mfma_f32_16x16x32_bf16 v[118:121], v[188:191], v[204:207], v[118:121]
	v_mfma_f32_16x16x32_bf16 v[114:117], v[196:199], v[204:207], v[114:117]
	v_mfma_f32_16x16x32_bf16 v[102:105], v[188:191], v[212:215], v[102:105]
	v_mfma_f32_16x16x32_bf16 v[98:101], v[196:199], v[212:215], v[98:101]
	v_mfma_f32_16x16x32_bf16 v[86:89], v[188:191], v[220:223], v[86:89]
	v_mfma_f32_16x16x32_bf16 v[82:85], v[196:199], v[220:223], v[82:85]
	v_mfma_f32_16x16x32_bf16 v[70:73], v[188:191], v[228:231], v[70:73]
	v_mfma_f32_16x16x32_bf16 v[66:69], v[196:199], v[228:231], v[66:69]
	v_mfma_f32_16x16x32_bf16 v[118:121], v[192:195], v[208:211], v[118:121]
	v_mfma_f32_16x16x32_bf16 v[114:117], v[200:203], v[208:211], v[114:117]
	v_mfma_f32_16x16x32_bf16 v[102:105], v[192:195], v[216:219], v[102:105]
	v_mfma_f32_16x16x32_bf16 v[98:101], v[200:203], v[216:219], v[98:101]
	v_mfma_f32_16x16x32_bf16 v[86:89], v[192:195], v[224:227], v[86:89]
	v_mfma_f32_16x16x32_bf16 v[82:85], v[200:203], v[224:227], v[82:85]
	v_mfma_f32_16x16x32_bf16 v[70:73], v[192:195], v[232:235], v[70:73]
	v_mfma_f32_16x16x32_bf16 v[66:69], v[200:203], v[232:235], v[66:69]
	s_barrier
	s_add_i32 s10, s31, s20
	v_lshl_add_u64 v[148:149], v[148:149], 0, s[94:95]
	s_mov_b32 m0, s10
	ds_read_b128 v[204:207], v172 offset:49152
	ds_read_b128 v[208:211], v172 offset:50176
	ds_read_b128 v[212:215], v172 offset:51200
	ds_read_b128 v[216:219], v172 offset:52224
	ds_read_b128 v[220:223], v172 offset:53248
	ds_read_b128 v[224:227], v172 offset:54272
	ds_read_b128 v[228:231], v172 offset:55296
	ds_read_b128 v[232:235], v172 offset:56320
	global_load_lds_dwordx4 v[148:149], off
	v_lshl_add_u64 v[148:149], v[236:237], 0, s[94:95]
	s_add_i32 m0, s10, 0x2000
	s_add_i32 s10, s35, s20
	global_load_lds_dwordx4 v[148:149], off
	v_lshl_add_u64 v[148:149], v[238:239], 0, s[94:95]
	s_mov_b32 m0, s10
	s_nop 0
	global_load_lds_dwordx4 v[148:149], off
	v_lshl_add_u64 v[148:149], v[240:241], 0, s[94:95]
	s_add_i32 m0, s10, 0x2000
	s_nop 0
	global_load_lds_dwordx4 v[148:149], off
	v_lshl_add_u64 v[148:149], v[242:243], 0, s[94:95]
	s_mov_b32 m0, s56
	s_nop 0
	global_load_lds_dwordx4 v[148:149], off
	v_lshl_add_u64 v[148:149], v[244:245], 0, s[94:95]
	s_mov_b32 m0, s57
	s_nop 0
	global_load_lds_dwordx4 v[148:149], off
	s_waitcnt vmcnt(8)
	s_waitcnt lgkmcnt(0)
	s_barrier
	s_waitcnt lgkmcnt(0)
	v_mfma_f32_16x16x32_bf16 v[62:65], v[140:143], v[204:207], v[62:65]
	v_mfma_f32_16x16x32_bf16 v[58:61], v[180:183], v[204:207], v[58:61]
	v_mfma_f32_16x16x32_bf16 v[46:49], v[140:143], v[212:215], v[46:49]
	v_mfma_f32_16x16x32_bf16 v[42:45], v[180:183], v[212:215], v[42:45]
	v_mfma_f32_16x16x32_bf16 v[30:33], v[140:143], v[220:223], v[30:33]
	v_mfma_f32_16x16x32_bf16 v[26:29], v[180:183], v[220:223], v[26:29]
	v_mfma_f32_16x16x32_bf16 v[14:17], v[140:143], v[228:231], v[14:17]
	v_mfma_f32_16x16x32_bf16 v[10:13], v[180:183], v[228:231], v[10:13]
	v_mfma_f32_16x16x32_bf16 v[62:65], v[144:147], v[208:211], v[62:65]
	v_mfma_f32_16x16x32_bf16 v[58:61], v[184:187], v[208:211], v[58:61]
	v_mfma_f32_16x16x32_bf16 v[46:49], v[144:147], v[216:219], v[46:49]
	v_mfma_f32_16x16x32_bf16 v[42:45], v[184:187], v[216:219], v[42:45]
	v_mfma_f32_16x16x32_bf16 v[30:33], v[144:147], v[224:227], v[30:33]
	v_mfma_f32_16x16x32_bf16 v[26:29], v[184:187], v[224:227], v[26:29]
	v_mfma_f32_16x16x32_bf16 v[14:17], v[144:147], v[232:235], v[14:17]
	v_mfma_f32_16x16x32_bf16 v[10:13], v[184:187], v[232:235], v[10:13]
	v_mfma_f32_16x16x32_bf16 v[54:57], v[188:191], v[204:207], v[54:57]
	v_mfma_f32_16x16x32_bf16 v[50:53], v[196:199], v[204:207], v[50:53]
	v_mfma_f32_16x16x32_bf16 v[38:41], v[188:191], v[212:215], v[38:41]
	v_mfma_f32_16x16x32_bf16 v[34:37], v[196:199], v[212:215], v[34:37]
	v_mfma_f32_16x16x32_bf16 v[22:25], v[188:191], v[220:223], v[22:25]
	v_mfma_f32_16x16x32_bf16 v[18:21], v[196:199], v[220:223], v[18:21]
	v_mfma_f32_16x16x32_bf16 v[6:9], v[188:191], v[228:231], v[6:9]
	v_mfma_f32_16x16x32_bf16 v[2:5], v[196:199], v[228:231], v[2:5]
	v_mfma_f32_16x16x32_bf16 v[54:57], v[192:195], v[208:211], v[54:57]
	v_mfma_f32_16x16x32_bf16 v[50:53], v[200:203], v[208:211], v[50:53]
	v_mfma_f32_16x16x32_bf16 v[38:41], v[192:195], v[216:219], v[38:41]
	v_mfma_f32_16x16x32_bf16 v[34:37], v[200:203], v[216:219], v[34:37]
	v_mfma_f32_16x16x32_bf16 v[22:25], v[192:195], v[224:227], v[22:25]
	v_mfma_f32_16x16x32_bf16 v[18:21], v[200:203], v[224:227], v[18:21]
	v_mfma_f32_16x16x32_bf16 v[6:9], v[192:195], v[232:235], v[6:9]
	v_mfma_f32_16x16x32_bf16 v[2:5], v[200:203], v[232:235], v[2:5]
	s_barrier
	s_add_u32 s2, s2, 0x100
	s_addc_u32 s3, s3, 0
	s_add_u32 s19, s19, 0x100
	s_addc_u32 s29, s29, 0
	s_cmp_ge_u32 s30, s55
	s_mov_b32 s10, s30
	s_cbranch_scc0 .LBB0_360
	s_and_b64 vcc, exec, s[14:15]
	s_cbranch_vccz .LBB0_363
	s_barrier

.LBB0_397:
	s_and_b64 vcc, exec, s[8:9]
	s_mov_b64 s[2:3], -1
	s_cbranch_vccnz .LBB0_351
	v_lshl_add_u32 v2, s64, 8, v162
	v_ashrrev_i32_e32 v3, 31, v2
	s_mov_b32 m0, s21
	v_lshl_add_u64 v[2:3], v[2:3], 4, s[98:99]
	s_mov_b64 s[2:3], 0x800
	global_load_lds_dwordx4 v[2:3], off
	v_lshl_add_u64 v[2:3], v[2:3], 0, s[2:3]
	s_add_i32 m0, s21, 0x400
	v_readlane_b32 s2, v248, 29
	global_load_lds_dwordx4 v[2:3], off
	v_readlane_b32 s3, v248, 30
	s_andn2_b64 vcc, exec, s[2:3]
	s_cbranch_vccnz .LBB0_350
	s_mov_b32 s100, 1
	s_branch .LBB0_350

.Ldb_419:
.LBB0_419:
	s_add_i32 s66, s20, 2
	s_add_u32 s67, s16, 0x80
	s_addc_u32 s21, s17, 0
	s_add_i32 s72, 0, 0x10000
	s_cmp_eq_u32 s58, s20
	s_cselect_b32 s21, s1, s21
	s_cselect_b32 s20, s0, s67
	v_add_u32_e32 v140, s72, v143
	s_cselect_b32 s71, s15, s65
	s_cselect_b32 s70, s14, s64
	s_add_i32 s67, 0, 0x14000
	ds_read_b128 v[160:163], v140
	ds_read_b128 v[164:167], v140 offset:1024
	ds_read_b128 v[168:171], v140 offset:2048
	ds_read_b128 v[172:175], v140 offset:3072
	v_add_u32_e32 v140, s67, v143
	ds_read_b128 v[176:179], v140
	ds_read_b128 v[180:183], v140 offset:1024
	ds_read_b128 v[184:187], v140 offset:2048
	ds_read_b128 v[188:191], v140 offset:3072
	v_lshl_add_u64 v[140:141], s[16:17], 0, v[136:137]
	s_add_i32 m0, s35, 0xc000
	ds_read_b128 v[192:195], v146
	ds_read_b128 v[196:199], v146 offset:1024
	ds_read_b128 v[200:203], v146 offset:2048
	ds_read_b128 v[204:207], v146 offset:3072
	ds_read_b128 v[208:211], v146 offset:4096
	ds_read_b128 v[212:215], v146 offset:5120
	ds_read_b128 v[216:219], v146 offset:6144
	ds_read_b128 v[220:223], v146 offset:7168
	global_load_lds_dwordx4 v[140:141], off
	v_lshl_add_u64 v[140:141], s[16:17], 0, v[138:139]
	s_add_i32 m0, s35, 0xe000
	s_nop 0
	global_load_lds_dwordx4 v[140:141], off
	s_waitcnt vmcnt(8)
	s_waitcnt lgkmcnt(0)
	s_barrier
	s_waitcnt lgkmcnt(0)
	v_mfma_f32_16x16x32_bf16 v[126:129], v[160:163], v[192:195], v[126:129]
	v_mfma_f32_16x16x32_bf16 v[122:125], v[168:171], v[192:195], v[122:125]
	v_mfma_f32_16x16x32_bf16 v[110:113], v[160:163], v[200:203], v[110:113]
	v_mfma_f32_16x16x32_bf16 v[106:109], v[168:171], v[200:203], v[106:109]
	v_mfma_f32_16x16x32_bf16 v[94:97], v[160:163], v[208:211], v[94:97]
	v_mfma_f32_16x16x32_bf16 v[90:93], v[168:171], v[208:211], v[90:93]
	v_mfma_f32_16x16x32_bf16 v[78:81], v[160:163], v[216:219], v[78:81]
	v_mfma_f32_16x16x32_bf16 v[74:77], v[168:171], v[216:219], v[74:77]
	v_mfma_f32_16x16x32_bf16 v[126:129], v[164:167], v[196:199], v[126:129]
	v_mfma_f32_16x16x32_bf16 v[122:125], v[172:175], v[196:199], v[122:125]
	v_mfma_f32_16x16x32_bf16 v[110:113], v[164:167], v[204:207], v[110:113]
	v_mfma_f32_16x16x32_bf16 v[106:109], v[172:175], v[204:207], v[106:109]
	v_mfma_f32_16x16x32_bf16 v[94:97], v[164:167], v[212:215], v[94:97]
	v_mfma_f32_16x16x32_bf16 v[90:93], v[172:175], v[212:215], v[90:93]
	v_mfma_f32_16x16x32_bf16 v[78:81], v[164:167], v[220:223], v[78:81]
	v_mfma_f32_16x16x32_bf16 v[74:77], v[172:175], v[220:223], v[74:77]
	v_mfma_f32_16x16x32_bf16 v[118:121], v[176:179], v[192:195], v[118:121]
	v_mfma_f32_16x16x32_bf16 v[114:117], v[184:187], v[192:195], v[114:117]
	v_mfma_f32_16x16x32_bf16 v[102:105], v[176:179], v[200:203], v[102:105]
	v_mfma_f32_16x16x32_bf16 v[98:101], v[184:187], v[200:203], v[98:101]
	v_mfma_f32_16x16x32_bf16 v[86:89], v[176:179], v[208:211], v[86:89]
	v_mfma_f32_16x16x32_bf16 v[82:85], v[184:187], v[208:211], v[82:85]
	v_mfma_f32_16x16x32_bf16 v[70:73], v[176:179], v[216:219], v[70:73]
	v_mfma_f32_16x16x32_bf16 v[66:69], v[184:187], v[216:219], v[66:69]
	v_mfma_f32_16x16x32_bf16 v[118:121], v[180:183], v[196:199], v[118:121]
	v_mfma_f32_16x16x32_bf16 v[114:117], v[188:191], v[196:199], v[114:117]
	v_mfma_f32_16x16x32_bf16 v[102:105], v[180:183], v[204:207], v[102:105]
	v_mfma_f32_16x16x32_bf16 v[98:101], v[188:191], v[204:207], v[98:101]
	v_mfma_f32_16x16x32_bf16 v[86:89], v[180:183], v[212:215], v[86:89]
	v_mfma_f32_16x16x32_bf16 v[82:85], v[188:191], v[212:215], v[82:85]
	v_mfma_f32_16x16x32_bf16 v[70:73], v[180:183], v[220:223], v[70:73]
	v_mfma_f32_16x16x32_bf16 v[66:69], v[188:191], v[220:223], v[66:69]
	s_barrier
	s_add_i32 s72, s72, s30
	v_lshl_add_u64 v[140:141], s[70:71], 0, v[0:1]
	s_mov_b32 m0, s72
	ds_read_b128 v[192:195], v146 offset:16384
	ds_read_b128 v[196:199], v146 offset:17408
	ds_read_b128 v[200:203], v146 offset:18432
	ds_read_b128 v[204:207], v146 offset:19456
	ds_read_b128 v[208:211], v146 offset:20480
	ds_read_b128 v[212:215], v146 offset:21504
	ds_read_b128 v[216:219], v146 offset:22528
	ds_read_b128 v[220:223], v146 offset:23552
	global_load_lds_dwordx4 v[140:141], off
	s_add_i32 m0, s72, 0x2000
	v_lshl_add_u64 v[148:149], s[70:71], 0, v[134:135]
	s_add_u32 s70, s70, s80
	s_addc_u32 s71, s71, 0
	s_add_i32 s67, s67, s30
	global_load_lds_dwordx4 v[148:149], off
	v_lshl_add_u64 v[224:225], s[70:71], 0, v[0:1]
	s_mov_b32 m0, s67
	v_lshl_add_u64 v[226:227], s[70:71], 0, v[134:135]
	global_load_lds_dwordx4 v[224:225], off
	s_add_i32 m0, s67, 0x2000
	v_lshl_add_u64 v[228:229], s[20:21], 0, v[130:131]
	global_load_lds_dwordx4 v[226:227], off
	s_mov_b32 m0, s35
	v_lshl_add_u64 v[230:231], s[20:21], 0, v[132:133]
	global_load_lds_dwordx4 v[228:229], off
	s_mov_b32 m0, s52
	s_nop 0
	global_load_lds_dwordx4 v[230:231], off
	s_waitcnt vmcnt(8)
	s_waitcnt lgkmcnt(0)
	s_barrier
	s_waitcnt lgkmcnt(0)
	v_mfma_f32_16x16x32_bf16 v[62:65], v[160:163], v[192:195], v[62:65]
	v_mfma_f32_16x16x32_bf16 v[58:61], v[168:171], v[192:195], v[58:61]
	v_mfma_f32_16x16x32_bf16 v[46:49], v[160:163], v[200:203], v[46:49]
	v_mfma_f32_16x16x32_bf16 v[42:45], v[168:171], v[200:203], v[42:45]
	v_mfma_f32_16x16x32_bf16 v[30:33], v[160:163], v[208:211], v[30:33]
	v_mfma_f32_16x16x32_bf16 v[26:29], v[168:171], v[208:211], v[26:29]
	v_mfma_f32_16x16x32_bf16 v[14:17], v[160:163], v[216:219], v[14:17]
	v_mfma_f32_16x16x32_bf16 v[10:13], v[168:171], v[216:219], v[10:13]
	v_mfma_f32_16x16x32_bf16 v[62:65], v[164:167], v[196:199], v[62:65]
	v_mfma_f32_16x16x32_bf16 v[58:61], v[172:175], v[196:199], v[58:61]
	v_mfma_f32_16x16x32_bf16 v[46:49], v[164:167], v[204:207], v[46:49]
	v_mfma_f32_16x16x32_bf16 v[42:45], v[172:175], v[204:207], v[42:45]
	v_mfma_f32_16x16x32_bf16 v[30:33], v[164:167], v[212:215], v[30:33]
	v_mfma_f32_16x16x32_bf16 v[26:29], v[172:175], v[212:215], v[26:29]
	v_mfma_f32_16x16x32_bf16 v[14:17], v[164:167], v[220:223], v[14:17]
	v_mfma_f32_16x16x32_bf16 v[10:13], v[172:175], v[220:223], v[10:13]
	v_mfma_f32_16x16x32_bf16 v[54:57], v[176:179], v[192:195], v[54:57]
	v_mfma_f32_16x16x32_bf16 v[50:53], v[184:187], v[192:195], v[50:53]
	v_mfma_f32_16x16x32_bf16 v[38:41], v[176:179], v[200:203], v[38:41]
	v_mfma_f32_16x16x32_bf16 v[34:37], v[184:187], v[200:203], v[34:37]
	v_mfma_f32_16x16x32_bf16 v[22:25], v[176:179], v[208:211], v[22:25]
	v_mfma_f32_16x16x32_bf16 v[18:21], v[184:187], v[208:211], v[18:21]
	v_mfma_f32_16x16x32_bf16 v[6:9], v[176:179], v[216:219], v[6:9]
	v_mfma_f32_16x16x32_bf16 v[2:5], v[184:187], v[216:219], v[2:5]
	v_mfma_f32_16x16x32_bf16 v[54:57], v[180:183], v[196:199], v[54:57]
	v_mfma_f32_16x16x32_bf16 v[50:53], v[188:191], v[196:199], v[50:53]
	v_mfma_f32_16x16x32_bf16 v[38:41], v[180:183], v[204:207], v[38:41]
	v_mfma_f32_16x16x32_bf16 v[34:37], v[188:191], v[204:207], v[34:37]
	v_mfma_f32_16x16x32_bf16 v[22:25], v[180:183], v[212:215], v[22:25]
	v_mfma_f32_16x16x32_bf16 v[18:21], v[188:191], v[212:215], v[18:21]
	v_mfma_f32_16x16x32_bf16 v[6:9], v[180:183], v[220:223], v[6:9]
	v_mfma_f32_16x16x32_bf16 v[2:5], v[188:191], v[220:223], v[2:5]
	s_barrier
	s_add_i32 s67, 0, 0x18000
	v_add_u32_e32 v159, s67, v143
	s_add_i32 s70, 0, 0x1c000
	ds_read_b128 v[160:163], v159
	ds_read_b128 v[164:167], v159 offset:1024
	ds_read_b128 v[168:171], v159 offset:2048
	ds_read_b128 v[172:175], v159 offset:3072
	v_add_u32_e32 v159, s70, v143
	ds_read_b128 v[176:179], v159
	ds_read_b128 v[180:183], v159 offset:1024
	ds_read_b128 v[184:187], v159 offset:2048
	ds_read_b128 v[188:191], v159 offset:3072
	s_add_u32 s20, s20, s80
	s_addc_u32 s21, s21, 0
	s_mov_b32 m0, s53
	v_lshl_add_u64 v[232:233], s[20:21], 0, v[130:131]
	ds_read_b128 v[192:195], v146 offset:32768
	ds_read_b128 v[196:199], v146 offset:33792
	ds_read_b128 v[200:203], v146 offset:34816
	ds_read_b128 v[204:207], v146 offset:35840
	ds_read_b128 v[208:211], v146 offset:36864
	ds_read_b128 v[212:215], v146 offset:37888
	ds_read_b128 v[216:219], v146 offset:38912
	ds_read_b128 v[220:223], v146 offset:39936
	global_load_lds_dwordx4 v[232:233], off
	v_lshl_add_u64 v[232:233], s[20:21], 0, v[132:133]
	s_mov_b32 m0, s54
	s_nop 0
	global_load_lds_dwordx4 v[232:233], off
	s_waitcnt vmcnt(8)
	s_waitcnt lgkmcnt(0)
	s_barrier
	s_waitcnt lgkmcnt(0)
	v_mfma_f32_16x16x32_bf16 v[126:129], v[160:163], v[192:195], v[126:129]
	v_mfma_f32_16x16x32_bf16 v[122:125], v[168:171], v[192:195], v[122:125]
	v_mfma_f32_16x16x32_bf16 v[110:113], v[160:163], v[200:203], v[110:113]
	v_mfma_f32_16x16x32_bf16 v[106:109], v[168:171], v[200:203], v[106:109]
	v_mfma_f32_16x16x32_bf16 v[94:97], v[160:163], v[208:211], v[94:97]
	v_mfma_f32_16x16x32_bf16 v[90:93], v[168:171], v[208:211], v[90:93]
	v_mfma_f32_16x16x32_bf16 v[78:81], v[160:163], v[216:219], v[78:81]
	v_mfma_f32_16x16x32_bf16 v[74:77], v[168:171], v[216:219], v[74:77]
	v_mfma_f32_16x16x32_bf16 v[126:129], v[164:167], v[196:199], v[126:129]
	v_mfma_f32_16x16x32_bf16 v[122:125], v[172:175], v[196:199], v[122:125]
	v_mfma_f32_16x16x32_bf16 v[110:113], v[164:167], v[204:207], v[110:113]
	v_mfma_f32_16x16x32_bf16 v[106:109], v[172:175], v[204:207], v[106:109]
	v_mfma_f32_16x16x32_bf16 v[94:97], v[164:167], v[212:215], v[94:97]
	v_mfma_f32_16x16x32_bf16 v[90:93], v[172:175], v[212:215], v[90:93]
	v_mfma_f32_16x16x32_bf16 v[78:81], v[164:167], v[220:223], v[78:81]
	v_mfma_f32_16x16x32_bf16 v[74:77], v[172:175], v[220:223], v[74:77]
	v_mfma_f32_16x16x32_bf16 v[118:121], v[176:179], v[192:195], v[118:121]
	v_mfma_f32_16x16x32_bf16 v[114:117], v[184:187], v[192:195], v[114:117]
	v_mfma_f32_16x16x32_bf16 v[102:105], v[176:179], v[200:203], v[102:105]
	v_mfma_f32_16x16x32_bf16 v[98:101], v[184:187], v[200:203], v[98:101]
	v_mfma_f32_16x16x32_bf16 v[86:89], v[176:179], v[208:211], v[86:89]
	v_mfma_f32_16x16x32_bf16 v[82:85], v[184:187], v[208:211], v[82:85]
	v_mfma_f32_16x16x32_bf16 v[70:73], v[176:179], v[216:219], v[70:73]
	v_mfma_f32_16x16x32_bf16 v[66:69], v[184:187], v[216:219], v[66:69]
	v_mfma_f32_16x16x32_bf16 v[118:121], v[180:183], v[196:199], v[118:121]
	v_mfma_f32_16x16x32_bf16 v[114:117], v[188:191], v[196:199], v[114:117]
	v_mfma_f32_16x16x32_bf16 v[102:105], v[180:183], v[204:207], v[102:105]
	v_mfma_f32_16x16x32_bf16 v[98:101], v[188:191], v[204:207], v[98:101]
	v_mfma_f32_16x16x32_bf16 v[86:89], v[180:183], v[212:215], v[86:89]
	v_mfma_f32_16x16x32_bf16 v[82:85], v[188:191], v[212:215], v[82:85]
	v_mfma_f32_16x16x32_bf16 v[70:73], v[180:183], v[220:223], v[70:73]
	v_mfma_f32_16x16x32_bf16 v[66:69], v[188:191], v[220:223], v[66:69]
	s_barrier
	s_add_i32 s20, s67, s30
	v_lshl_add_u64 v[140:141], v[140:141], 0, s[94:95]
	s_mov_b32 m0, s20
	ds_read_b128 v[192:195], v146 offset:49152
	ds_read_b128 v[196:199], v146 offset:50176
	ds_read_b128 v[200:203], v146 offset:51200
	ds_read_b128 v[204:207], v146 offset:52224
	ds_read_b128 v[208:211], v146 offset:53248
	ds_read_b128 v[212:215], v146 offset:54272
	ds_read_b128 v[216:219], v146 offset:55296
	ds_read_b128 v[220:223], v146 offset:56320
	global_load_lds_dwordx4 v[140:141], off
	v_lshl_add_u64 v[140:141], v[148:149], 0, s[94:95]
	s_add_i32 m0, s20, 0x2000
	s_add_i32 s20, s70, s30
	global_load_lds_dwordx4 v[140:141], off
	v_lshl_add_u64 v[140:141], v[224:225], 0, s[94:95]
	s_mov_b32 m0, s20
	s_nop 0
	global_load_lds_dwordx4 v[140:141], off
	v_lshl_add_u64 v[140:141], v[226:227], 0, s[94:95]
	s_add_i32 m0, s20, 0x2000
	s_nop 0
	global_load_lds_dwordx4 v[140:141], off
	v_lshl_add_u64 v[140:141], v[228:229], 0, s[94:95]
	s_mov_b32 m0, s55
	s_nop 0
	global_load_lds_dwordx4 v[140:141], off
	v_lshl_add_u64 v[140:141], v[230:231], 0, s[94:95]
	s_mov_b32 m0, s56
	s_nop 0
	global_load_lds_dwordx4 v[140:141], off
	s_waitcnt vmcnt(8)
	s_waitcnt lgkmcnt(0)
	s_barrier
	s_waitcnt lgkmcnt(0)
	v_mfma_f32_16x16x32_bf16 v[62:65], v[160:163], v[192:195], v[62:65]
	v_mfma_f32_16x16x32_bf16 v[58:61], v[168:171], v[192:195], v[58:61]
	v_mfma_f32_16x16x32_bf16 v[46:49], v[160:163], v[200:203], v[46:49]
	v_mfma_f32_16x16x32_bf16 v[42:45], v[168:171], v[200:203], v[42:45]
	v_mfma_f32_16x16x32_bf16 v[30:33], v[160:163], v[208:211], v[30:33]
	v_mfma_f32_16x16x32_bf16 v[26:29], v[168:171], v[208:211], v[26:29]
	v_mfma_f32_16x16x32_bf16 v[14:17], v[160:163], v[216:219], v[14:17]
	v_mfma_f32_16x16x32_bf16 v[10:13], v[168:171], v[216:219], v[10:13]
	v_mfma_f32_16x16x32_bf16 v[62:65], v[164:167], v[196:199], v[62:65]
	v_mfma_f32_16x16x32_bf16 v[58:61], v[172:175], v[196:199], v[58:61]
	v_mfma_f32_16x16x32_bf16 v[46:49], v[164:167], v[204:207], v[46:49]
	v_mfma_f32_16x16x32_bf16 v[42:45], v[172:175], v[204:207], v[42:45]
	v_mfma_f32_16x16x32_bf16 v[30:33], v[164:167], v[212:215], v[30:33]
	v_mfma_f32_16x16x32_bf16 v[26:29], v[172:175], v[212:215], v[26:29]
	v_mfma_f32_16x16x32_bf16 v[14:17], v[164:167], v[220:223], v[14:17]
	v_mfma_f32_16x16x32_bf16 v[10:13], v[172:175], v[220:223], v[10:13]
	v_mfma_f32_16x16x32_bf16 v[54:57], v[176:179], v[192:195], v[54:57]
	v_mfma_f32_16x16x32_bf16 v[50:53], v[184:187], v[192:195], v[50:53]
	v_mfma_f32_16x16x32_bf16 v[38:41], v[176:179], v[200:203], v[38:41]
	v_mfma_f32_16x16x32_bf16 v[34:37], v[184:187], v[200:203], v[34:37]
	v_mfma_f32_16x16x32_bf16 v[22:25], v[176:179], v[208:211], v[22:25]
	v_mfma_f32_16x16x32_bf16 v[18:21], v[184:187], v[208:211], v[18:21]
	v_mfma_f32_16x16x32_bf16 v[6:9], v[176:179], v[216:219], v[6:9]
	v_mfma_f32_16x16x32_bf16 v[2:5], v[184:187], v[216:219], v[2:5]
	v_mfma_f32_16x16x32_bf16 v[54:57], v[180:183], v[196:199], v[54:57]
	v_mfma_f32_16x16x32_bf16 v[50:53], v[188:191], v[196:199], v[50:53]
	v_mfma_f32_16x16x32_bf16 v[38:41], v[180:183], v[204:207], v[38:41]
	v_mfma_f32_16x16x32_bf16 v[34:37], v[188:191], v[204:207], v[34:37]
	v_mfma_f32_16x16x32_bf16 v[22:25], v[180:183], v[212:215], v[22:25]
	v_mfma_f32_16x16x32_bf16 v[18:21], v[188:191], v[212:215], v[18:21]
	v_mfma_f32_16x16x32_bf16 v[6:9], v[180:183], v[220:223], v[6:9]
	v_mfma_f32_16x16x32_bf16 v[2:5], v[188:191], v[220:223], v[2:5]
	s_barrier
	s_add_u32 s16, s16, 0x100
	s_addc_u32 s17, s17, 0
	s_add_u32 s64, s64, 0x100
	s_addc_u32 s65, s65, 0
	s_cmp_ge_u32 s66, s57
	s_mov_b32 s20, s66
	s_cbranch_scc0 .LBB0_419
	s_and_b64 vcc, exec, s[10:11]
	s_cbranch_vccz .LBB0_422
	s_barrier
.LBB0_422:
	ds_read_b128 v[160:163], v147
	v_lshl_add_u32 v148, s62, 8, v142
	v_ashrrev_i32_e32 v149, 31, v148
	v_mul_lo_u32 v149, s68, v149
	v_mul_lo_u32 v159, s69, v148
	s_waitcnt lgkmcnt(0)
	v_mov_b32_e32 v166, v161
	v_mov_b32_e32 v167, v162
	v_mov_b32_e32 v161, v163
	v_mad_u64_u32 v[164:165], s[16:17], s68, v148, 0
	v_pk_add_f32 v[160:161], v[166:167], v[160:161]
	v_add3_u32 v165, v165, v149, v159
	v_add_f32_e32 v159, v160, v161
	v_fmamk_f32 v159, v159, 0x3a800000, v155
	v_rsq_f32_e32 v160, v159
	v_lshl_or_b32 v140, s63, 8, v144
	v_ashrrev_i32_e32 v141, 31, v140
	v_lshl_add_u64 v[162:163], v[164:165], 1, s[78:79]
	v_lshlrev_b64 v[140:141], 1, v[140:141]
	v_lshl_add_u64 v[162:163], v[162:163], 0, v[140:141]
	v_pk_mul_f32 v[128:129], v[128:129], v[160:161] op_sel_hi:[1,0]
	v_pk_mul_f32 v[126:127], v[126:127], v[160:161] op_sel_hi:[1,0]
	v_pk_mul_f32 v[164:165], v[124:125], v[160:161] op_sel_hi:[1,0]
	v_pk_mul_f32 v[124:125], v[122:123], v[160:161] op_sel_hi:[1,0]
	v_cvt_pk_bf16_f32 v122, v126, v127
	v_cvt_pk_bf16_f32 v123, v128, v129
	v_pk_mul_f32 v[120:121], v[120:121], v[160:161] op_sel_hi:[1,0]
	v_cvt_pk_bf16_f32 v124, v124, v125
	v_cvt_pk_bf16_f32 v125, v164, v165
	global_store_dwordx4 v[162:163], v[122:125], off
	v_pk_mul_f32 v[118:119], v[118:119], v[160:161] op_sel_hi:[1,0]
	s_and_b64 vcc, exec, s[6:7]
	v_pk_mul_f32 v[122:123], v[116:117], v[160:161] op_sel_hi:[1,0]
	v_pk_mul_f32 v[116:117], v[114:115], v[160:161] op_sel_hi:[1,0]
	v_cvt_pk_bf16_f32 v114, v118, v119
	v_cvt_pk_bf16_f32 v115, v120, v121
	v_or_b32_e32 v118, 16, v148
	v_cvt_pk_bf16_f32 v116, v116, v117
	v_cvt_pk_bf16_f32 v117, v122, v123
	global_store_dwordx4 v[162:163], v[114:117], off offset:256
	ds_read_b128 v[114:117], v147 offset:256
	v_mul_lo_u32 v122, s69, v118
	v_mad_u64_u32 v[118:119], s[16:17], s68, v118, 0
	v_add3_u32 v119, v119, v149, v122
	s_waitcnt lgkmcnt(0)
	v_mov_b32_e32 v120, v115
	v_mov_b32_e32 v121, v116
	v_mov_b32_e32 v115, v117
	v_pk_add_f32 v[114:115], v[120:121], v[114:115]
	v_lshl_add_u64 v[116:117], v[118:119], 1, s[78:79]
	v_add_f32_e32 v114, v114, v115
	v_fmamk_f32 v114, v114, 0x3a800000, v155
	v_rsq_f32_e32 v114, v114
	v_lshl_add_u64 v[116:117], v[116:117], 0, v[140:141]
	s_mov_b64 s[6:7], -1
	v_pk_mul_f32 v[112:113], v[112:113], v[114:115] op_sel_hi:[1,0]
	v_pk_mul_f32 v[110:111], v[110:111], v[114:115] op_sel_hi:[1,0]
	v_pk_mul_f32 v[118:119], v[108:109], v[114:115] op_sel_hi:[1,0]
	v_pk_mul_f32 v[108:109], v[106:107], v[114:115] op_sel_hi:[1,0]
	v_cvt_pk_bf16_f32 v106, v110, v111
	v_cvt_pk_bf16_f32 v107, v112, v113
	v_pk_mul_f32 v[104:105], v[104:105], v[114:115] op_sel_hi:[1,0]
	v_cvt_pk_bf16_f32 v108, v108, v109
	v_cvt_pk_bf16_f32 v109, v118, v119
	global_store_dwordx4 v[116:117], v[106:109], off
	v_pk_mul_f32 v[102:103], v[102:103], v[114:115] op_sel_hi:[1,0]
	s_nop 0
	v_pk_mul_f32 v[106:107], v[100:101], v[114:115] op_sel_hi:[1,0]
	v_pk_mul_f32 v[100:101], v[98:99], v[114:115] op_sel_hi:[1,0]
	v_cvt_pk_bf16_f32 v98, v102, v103
	v_cvt_pk_bf16_f32 v99, v104, v105
	v_or_b32_e32 v102, 32, v148
	v_cvt_pk_bf16_f32 v100, v100, v101
	v_cvt_pk_bf16_f32 v101, v106, v107
	global_store_dwordx4 v[116:117], v[98:101], off offset:256
	ds_read_b128 v[98:101], v147 offset:512
	v_mul_lo_u32 v106, s69, v102
	v_mad_u64_u32 v[102:103], s[16:17], s68, v102, 0
	v_add3_u32 v103, v103, v149, v106
	s_waitcnt lgkmcnt(0)
	v_mov_b32_e32 v104, v99
	v_mov_b32_e32 v105, v100
	v_mov_b32_e32 v99, v101
	v_pk_add_f32 v[98:99], v[104:105], v[98:99]
	v_lshl_add_u64 v[100:101], v[102:103], 1, s[78:79]
	v_add_f32_e32 v98, v98, v99
	v_fmamk_f32 v98, v98, 0x3a800000, v155
	v_rsq_f32_e32 v98, v98
	v_lshl_add_u64 v[100:101], v[100:101], 0, v[140:141]
	v_pk_mul_f32 v[96:97], v[96:97], v[98:99] op_sel_hi:[1,0]
	v_pk_mul_f32 v[94:95], v[94:95], v[98:99] op_sel_hi:[1,0]
	v_pk_mul_f32 v[102:103], v[92:93], v[98:99] op_sel_hi:[1,0]
	v_pk_mul_f32 v[92:93], v[90:91], v[98:99] op_sel_hi:[1,0]
	v_cvt_pk_bf16_f32 v90, v94, v95
	v_cvt_pk_bf16_f32 v91, v96, v97
	v_pk_mul_f32 v[88:89], v[88:89], v[98:99] op_sel_hi:[1,0]
	v_cvt_pk_bf16_f32 v92, v92, v93
	v_cvt_pk_bf16_f32 v93, v102, v103
	global_store_dwordx4 v[100:101], v[90:93], off
	v_pk_mul_f32 v[86:87], v[86:87], v[98:99] op_sel_hi:[1,0]
	s_nop 0
	v_pk_mul_f32 v[90:91], v[84:85], v[98:99] op_sel_hi:[1,0]
	v_pk_mul_f32 v[84:85], v[82:83], v[98:99] op_sel_hi:[1,0]
	v_cvt_pk_bf16_f32 v82, v86, v87
	v_cvt_pk_bf16_f32 v83, v88, v89
	v_or_b32_e32 v86, 48, v148
	v_cvt_pk_bf16_f32 v84, v84, v85
	v_cvt_pk_bf16_f32 v85, v90, v91
	global_store_dwordx4 v[100:101], v[82:85], off offset:256
	ds_read_b128 v[82:85], v147 offset:768
	v_mul_lo_u32 v90, s69, v86
	v_mad_u64_u32 v[86:87], s[16:17], s68, v86, 0
	v_add3_u32 v87, v87, v149, v90
	s_waitcnt lgkmcnt(0)
	v_mov_b32_e32 v88, v83
	v_mov_b32_e32 v89, v84
	v_mov_b32_e32 v83, v85
	v_pk_add_f32 v[82:83], v[88:89], v[82:83]
	v_lshl_add_u64 v[84:85], v[86:87], 1, s[78:79]
	v_add_f32_e32 v82, v82, v83
	v_fmamk_f32 v82, v82, 0x3a800000, v155
	v_rsq_f32_e32 v82, v82
	v_lshl_add_u64 v[84:85], v[84:85], 0, v[140:141]
	v_pk_mul_f32 v[80:81], v[80:81], v[82:83] op_sel_hi:[1,0]
	v_pk_mul_f32 v[78:79], v[78:79], v[82:83] op_sel_hi:[1,0]
	v_pk_mul_f32 v[86:87], v[76:77], v[82:83] op_sel_hi:[1,0]
	v_pk_mul_f32 v[76:77], v[74:75], v[82:83] op_sel_hi:[1,0]
	v_cvt_pk_bf16_f32 v74, v78, v79
	v_cvt_pk_bf16_f32 v75, v80, v81
	v_pk_mul_f32 v[72:73], v[72:73], v[82:83] op_sel_hi:[1,0]
	v_cvt_pk_bf16_f32 v76, v76, v77
	v_cvt_pk_bf16_f32 v77, v86, v87
	global_store_dwordx4 v[84:85], v[74:77], off
	v_pk_mul_f32 v[70:71], v[70:71], v[82:83] op_sel_hi:[1,0]
	s_nop 0
	v_pk_mul_f32 v[74:75], v[68:69], v[82:83] op_sel_hi:[1,0]
	v_pk_mul_f32 v[68:69], v[66:67], v[82:83] op_sel_hi:[1,0]
	v_cvt_pk_bf16_f32 v66, v70, v71
	v_cvt_pk_bf16_f32 v67, v72, v73
	v_add_u32_e32 v70, 0x80, v148
	v_cvt_pk_bf16_f32 v68, v68, v69
	v_cvt_pk_bf16_f32 v69, v74, v75
	global_store_dwordx4 v[84:85], v[66:69], off offset:256
	ds_read_b128 v[66:69], v147 offset:1024
	v_ashrrev_i32_e32 v71, 31, v70
	v_mul_lo_u32 v74, s68, v71
	v_mul_lo_u32 v75, s69, v70
	v_mad_u64_u32 v[70:71], s[16:17], s68, v70, 0
	s_waitcnt lgkmcnt(0)
	v_mov_b32_e32 v72, v67
	v_mov_b32_e32 v73, v68
	v_mov_b32_e32 v67, v69
	v_pk_add_f32 v[66:67], v[72:73], v[66:67]
	v_add3_u32 v71, v71, v74, v75
	v_add_f32_e32 v66, v66, v67
	v_fmamk_f32 v66, v66, 0x3a800000, v155
	v_rsq_f32_e32 v66, v66
	v_lshl_add_u64 v[68:69], v[70:71], 1, s[78:79]
	v_lshl_add_u64 v[68:69], v[68:69], 0, v[140:141]
	v_pk_mul_f32 v[64:65], v[64:65], v[66:67] op_sel_hi:[1,0]
	v_pk_mul_f32 v[62:63], v[62:63], v[66:67] op_sel_hi:[1,0]
	v_pk_mul_f32 v[70:71], v[60:61], v[66:67] op_sel_hi:[1,0]
	v_pk_mul_f32 v[60:61], v[58:59], v[66:67] op_sel_hi:[1,0]
	v_cvt_pk_bf16_f32 v58, v62, v63
	v_cvt_pk_bf16_f32 v59, v64, v65
	v_pk_mul_f32 v[56:57], v[56:57], v[66:67] op_sel_hi:[1,0]
	v_cvt_pk_bf16_f32 v60, v60, v61
	v_cvt_pk_bf16_f32 v61, v70, v71
	global_store_dwordx4 v[68:69], v[58:61], off
	v_pk_mul_f32 v[54:55], v[54:55], v[66:67] op_sel_hi:[1,0]
	s_nop 0
	v_pk_mul_f32 v[58:59], v[52:53], v[66:67] op_sel_hi:[1,0]
	v_pk_mul_f32 v[52:53], v[50:51], v[66:67] op_sel_hi:[1,0]
	v_cvt_pk_bf16_f32 v50, v54, v55
	v_cvt_pk_bf16_f32 v51, v56, v57
	v_add_u32_e32 v54, 0x90, v148
	v_cvt_pk_bf16_f32 v52, v52, v53
	v_cvt_pk_bf16_f32 v53, v58, v59
	global_store_dwordx4 v[68:69], v[50:53], off offset:256
	ds_read_b128 v[50:53], v147 offset:1280
	v_ashrrev_i32_e32 v55, 31, v54
	v_mul_lo_u32 v58, s68, v55
	v_mul_lo_u32 v59, s69, v54
	v_mad_u64_u32 v[54:55], s[16:17], s68, v54, 0
	s_waitcnt lgkmcnt(0)
	v_mov_b32_e32 v56, v51
	v_mov_b32_e32 v57, v52
	v_mov_b32_e32 v51, v53
	v_pk_add_f32 v[50:51], v[56:57], v[50:51]
	v_add3_u32 v55, v55, v58, v59
	v_add_f32_e32 v50, v50, v51
	v_fmamk_f32 v50, v50, 0x3a800000, v155
	v_rsq_f32_e32 v50, v50
	v_lshl_add_u64 v[52:53], v[54:55], 1, s[78:79]
	v_lshl_add_u64 v[52:53], v[52:53], 0, v[140:141]
	v_pk_mul_f32 v[48:49], v[48:49], v[50:51] op_sel_hi:[1,0]
	v_pk_mul_f32 v[46:47], v[46:47], v[50:51] op_sel_hi:[1,0]
	v_pk_mul_f32 v[54:55], v[44:45], v[50:51] op_sel_hi:[1,0]
	v_pk_mul_f32 v[44:45], v[42:43], v[50:51] op_sel_hi:[1,0]
	v_cvt_pk_bf16_f32 v42, v46, v47
	v_cvt_pk_bf16_f32 v43, v48, v49
	v_pk_mul_f32 v[40:41], v[40:41], v[50:51] op_sel_hi:[1,0]
	v_cvt_pk_bf16_f32 v44, v44, v45
	v_cvt_pk_bf16_f32 v45, v54, v55
	global_store_dwordx4 v[52:53], v[42:45], off
	v_pk_mul_f32 v[38:39], v[38:39], v[50:51] op_sel_hi:[1,0]
	s_nop 0
	v_pk_mul_f32 v[42:43], v[36:37], v[50:51] op_sel_hi:[1,0]
	v_pk_mul_f32 v[36:37], v[34:35], v[50:51] op_sel_hi:[1,0]
	v_cvt_pk_bf16_f32 v34, v38, v39
	v_cvt_pk_bf16_f32 v35, v40, v41
	v_add_u32_e32 v38, 0xa0, v148
	v_cvt_pk_bf16_f32 v36, v36, v37
	v_cvt_pk_bf16_f32 v37, v42, v43
	global_store_dwordx4 v[52:53], v[34:37], off offset:256
	ds_read_b128 v[34:37], v147 offset:1536
	v_ashrrev_i32_e32 v39, 31, v38
	v_mul_lo_u32 v42, s68, v39
	v_mul_lo_u32 v43, s69, v38
	v_mad_u64_u32 v[38:39], s[16:17], s68, v38, 0
	s_waitcnt lgkmcnt(0)
	v_mov_b32_e32 v40, v35
	v_mov_b32_e32 v41, v36
	v_mov_b32_e32 v35, v37
	v_pk_add_f32 v[34:35], v[40:41], v[34:35]
	v_add3_u32 v39, v39, v42, v43
	v_add_f32_e32 v34, v34, v35
	v_fmamk_f32 v34, v34, 0x3a800000, v155
	v_rsq_f32_e32 v34, v34
	v_lshl_add_u64 v[36:37], v[38:39], 1, s[78:79]
	v_lshl_add_u64 v[36:37], v[36:37], 0, v[140:141]
	v_pk_mul_f32 v[32:33], v[32:33], v[34:35] op_sel_hi:[1,0]
	v_pk_mul_f32 v[30:31], v[30:31], v[34:35] op_sel_hi:[1,0]
	v_pk_mul_f32 v[38:39], v[28:29], v[34:35] op_sel_hi:[1,0]
	v_pk_mul_f32 v[28:29], v[26:27], v[34:35] op_sel_hi:[1,0]
	v_cvt_pk_bf16_f32 v26, v30, v31
	v_cvt_pk_bf16_f32 v27, v32, v33
	v_pk_mul_f32 v[24:25], v[24:25], v[34:35] op_sel_hi:[1,0]
	v_cvt_pk_bf16_f32 v28, v28, v29
	v_cvt_pk_bf16_f32 v29, v38, v39
	global_store_dwordx4 v[36:37], v[26:29], off
	v_pk_mul_f32 v[22:23], v[22:23], v[34:35] op_sel_hi:[1,0]
	s_nop 0
	v_pk_mul_f32 v[26:27], v[20:21], v[34:35] op_sel_hi:[1,0]
	v_pk_mul_f32 v[20:21], v[18:19], v[34:35] op_sel_hi:[1,0]
	v_cvt_pk_bf16_f32 v18, v22, v23
	v_cvt_pk_bf16_f32 v19, v24, v25
	v_add_u32_e32 v22, 0xb0, v148
	v_cvt_pk_bf16_f32 v20, v20, v21
	v_cvt_pk_bf16_f32 v21, v26, v27
	global_store_dwordx4 v[36:37], v[18:21], off offset:256
	ds_read_b128 v[18:21], v147 offset:1792
	v_ashrrev_i32_e32 v23, 31, v22
	v_mul_lo_u32 v26, s68, v23
	v_mul_lo_u32 v27, s69, v22
	v_mad_u64_u32 v[22:23], s[16:17], s68, v22, 0
	s_waitcnt lgkmcnt(0)
	v_mov_b32_e32 v24, v19
	v_mov_b32_e32 v25, v20
	v_mov_b32_e32 v19, v21
	v_pk_add_f32 v[18:19], v[24:25], v[18:19]
	v_add3_u32 v23, v23, v26, v27
	v_add_f32_e32 v18, v18, v19
	v_fmamk_f32 v18, v18, 0x3a800000, v155
	v_rsq_f32_e32 v18, v18
	v_lshl_add_u64 v[20:21], v[22:23], 1, s[78:79]
	v_lshl_add_u64 v[20:21], v[20:21], 0, v[140:141]
	v_pk_mul_f32 v[16:17], v[16:17], v[18:19] op_sel_hi:[1,0]
	v_pk_mul_f32 v[14:15], v[14:15], v[18:19] op_sel_hi:[1,0]
	v_pk_mul_f32 v[22:23], v[12:13], v[18:19] op_sel_hi:[1,0]
	v_pk_mul_f32 v[12:13], v[10:11], v[18:19] op_sel_hi:[1,0]
	v_cvt_pk_bf16_f32 v10, v14, v15
	v_cvt_pk_bf16_f32 v11, v16, v17
	v_pk_mul_f32 v[8:9], v[8:9], v[18:19] op_sel_hi:[1,0]
	v_cvt_pk_bf16_f32 v12, v12, v13
	v_cvt_pk_bf16_f32 v13, v22, v23
	global_store_dwordx4 v[20:21], v[10:13], off
	v_pk_mul_f32 v[6:7], v[6:7], v[18:19] op_sel_hi:[1,0]
	s_nop 0
	v_pk_mul_f32 v[10:11], v[4:5], v[18:19] op_sel_hi:[1,0]
	v_pk_mul_f32 v[4:5], v[2:3], v[18:19] op_sel_hi:[1,0]
	v_cvt_pk_bf16_f32 v2, v6, v7
	v_cvt_pk_bf16_f32 v3, v8, v9
	s_nop 0
	v_cvt_pk_bf16_f32 v4, v4, v5
	v_cvt_pk_bf16_f32 v5, v10, v11
	global_store_dwordx4 v[20:21], v[2:5], off offset:256
	s_cbranch_vccnz .LBB0_410
	s_nop 0
	v_lshl_add_u32 v2, s61, 8, v145
	v_ashrrev_i32_e32 v3, 31, v2
	s_mov_b32 m0, s31
	v_lshl_add_u64 v[2:3], v[2:3], 4, s[96:97]
	global_load_lds_dwordx4 v[2:3], off
	v_lshl_add_u64 v[2:3], v[2:3], 0, s[82:83]
	s_add_i32 m0, s31, 0x400
	s_andn2_b64 vcc, exec, s[8:9]
	global_load_lds_dwordx4 v[2:3], off
	s_cbranch_vccnz .LBB0_409
	s_mov_b32 s100, 1
	s_branch .LBB0_409
